# GEMM epilogues with loads (merge A/B incl. sample pieces, w_o/w_xo/ff2 residual): serial load-wait-store chains replaced by batched loads + counted vmcnt
# speedup vs baseline: 1.1022x; 1.0166x over previous
.LBB0_1239:
	s_add_i32 s56, s55, 2
	s_add_u32 s57, vcc_lo, 0xfff80080
	s_addc_u32 s60, vcc_hi, -1
	s_add_i32 s68, 0, 0x10000
	v_add_u32_e32 v154, s68, v159
	ds_read_b128 v[142:145], v154
	ds_read_b128 v[146:149], v154 offset:1024
	ds_read_b128 v[150:153], v154 offset:2048
	ds_read_b128 v[154:157], v154 offset:3072
	s_cmp_eq_u32 s39, s55
	s_cselect_b32 s63, s23, s60
	s_cselect_b32 s62, s31, s57
	s_cselect_b32 s61, s29, s54
	s_cselect_b32 s60, s38, s53
	v_lshl_add_u64 v[196:197], vcc, 0, v[138:139]
	s_add_i32 m0, s27, 0xc000
	ds_read_b128 v[164:167], v162
	ds_read_b128 v[168:171], v162 offset:1024
	ds_read_b128 v[172:175], v162 offset:2048
	ds_read_b128 v[176:179], v162 offset:3072
	ds_read_b128 v[180:183], v162 offset:4096
	ds_read_b128 v[184:187], v162 offset:5120
	ds_read_b128 v[188:191], v162 offset:6144
	ds_read_b128 v[192:195], v162 offset:7168
	global_load_lds_dwordx4 v[196:197], off
	v_lshl_add_u64 v[196:197], vcc, 0, v[140:141]
	s_add_i32 m0, s27, 0xe000
	s_nop 0
	global_load_lds_dwordx4 v[196:197], off
	s_waitcnt lgkmcnt(8)
	s_barrier
	s_waitcnt lgkmcnt(0)
	s_setprio 1
	s_waitcnt lgkmcnt(0)
	v_mfma_f32_16x16x32_bf16 v[124:127], v[142:145], v[164:167], v[124:127]
	v_mfma_f32_16x16x32_bf16 v[120:123], v[150:153], v[164:167], v[120:123]
	v_mfma_f32_16x16x32_bf16 v[108:111], v[142:145], v[172:175], v[108:111]
	v_mfma_f32_16x16x32_bf16 v[104:107], v[150:153], v[172:175], v[104:107]
	v_mfma_f32_16x16x32_bf16 v[92:95], v[142:145], v[180:183], v[92:95]
	v_mfma_f32_16x16x32_bf16 v[88:91], v[150:153], v[180:183], v[88:91]
	v_mfma_f32_16x16x32_bf16 v[76:79], v[142:145], v[188:191], v[76:79]
	v_mfma_f32_16x16x32_bf16 v[72:75], v[150:153], v[188:191], v[72:75]
	v_mfma_f32_16x16x32_bf16 v[124:127], v[146:149], v[168:171], v[124:127]
	v_mfma_f32_16x16x32_bf16 v[120:123], v[154:157], v[168:171], v[120:123]
	v_mfma_f32_16x16x32_bf16 v[108:111], v[146:149], v[176:179], v[108:111]
	v_mfma_f32_16x16x32_bf16 v[104:107], v[154:157], v[176:179], v[104:107]
	v_mfma_f32_16x16x32_bf16 v[92:95], v[146:149], v[184:187], v[92:95]
	v_mfma_f32_16x16x32_bf16 v[88:91], v[154:157], v[184:187], v[88:91]
	v_mfma_f32_16x16x32_bf16 v[76:79], v[146:149], v[192:195], v[76:79]
	v_mfma_f32_16x16x32_bf16 v[72:75], v[154:157], v[192:195], v[72:75]
	s_setprio 0
	s_barrier
	s_add_i32 s55, 0, 0x14000
	s_add_i32 s57, s68, s41
	v_add_u32_e32 v163, s55, v159
	v_lshl_add_u64 v[212:213], s[60:61], 0, v[128:129]
	s_mov_b32 m0, s57
	ds_read_b128 v[196:199], v163
	ds_read_b128 v[200:203], v163 offset:1024
	ds_read_b128 v[204:207], v163 offset:2048
	ds_read_b128 v[208:211], v163 offset:3072
	global_load_lds_dwordx4 v[212:213], off
	v_lshl_add_u64 v[214:215], s[60:61], 0, v[136:137]
	s_add_i32 m0, s57, 0x2000
	s_nop 0
	global_load_lds_dwordx4 v[214:215], off
	s_barrier
	s_waitcnt lgkmcnt(0)
	s_setprio 1
	s_waitcnt lgkmcnt(0)
	v_mfma_f32_16x16x32_bf16 v[116:119], v[196:199], v[164:167], v[116:119]
	v_mfma_f32_16x16x32_bf16 v[112:115], v[204:207], v[164:167], v[112:115]
	v_mfma_f32_16x16x32_bf16 v[100:103], v[196:199], v[172:175], v[100:103]
	v_mfma_f32_16x16x32_bf16 v[96:99], v[204:207], v[172:175], v[96:99]
	v_mfma_f32_16x16x32_bf16 v[84:87], v[196:199], v[180:183], v[84:87]
	v_mfma_f32_16x16x32_bf16 v[80:83], v[204:207], v[180:183], v[80:83]
	v_mfma_f32_16x16x32_bf16 v[68:71], v[196:199], v[188:191], v[68:71]
	v_mfma_f32_16x16x32_bf16 v[64:67], v[204:207], v[188:191], v[64:67]
	v_mfma_f32_16x16x32_bf16 v[116:119], v[200:203], v[168:171], v[116:119]
	v_mfma_f32_16x16x32_bf16 v[112:115], v[208:211], v[168:171], v[112:115]
	v_mfma_f32_16x16x32_bf16 v[100:103], v[200:203], v[176:179], v[100:103]
	v_mfma_f32_16x16x32_bf16 v[96:99], v[208:211], v[176:179], v[96:99]
	v_mfma_f32_16x16x32_bf16 v[84:87], v[200:203], v[184:187], v[84:87]
	v_mfma_f32_16x16x32_bf16 v[80:83], v[208:211], v[184:187], v[80:83]
	v_mfma_f32_16x16x32_bf16 v[68:71], v[200:203], v[192:195], v[68:71]
	v_mfma_f32_16x16x32_bf16 v[64:67], v[208:211], v[192:195], v[64:67]
	s_setprio 0
	s_mov_b32 m0, s27
	v_lshl_add_u64 v[216:217], s[62:63], 0, v[132:133]
	s_barrier
	ds_read_b128 v[164:167], v162 offset:16384
	ds_read_b128 v[168:171], v162 offset:17408
	ds_read_b128 v[172:175], v162 offset:18432
	ds_read_b128 v[176:179], v162 offset:19456
	ds_read_b128 v[180:183], v162 offset:20480
	ds_read_b128 v[184:187], v162 offset:21504
	ds_read_b128 v[188:191], v162 offset:22528
	ds_read_b128 v[192:195], v162 offset:23552
	global_load_lds_dwordx4 v[216:217], off
	v_lshl_add_u64 v[218:219], s[62:63], 0, v[134:135]
	s_mov_b32 m0, s44
	s_nop 0
	global_load_lds_dwordx4 v[218:219], off
	s_barrier
	s_waitcnt lgkmcnt(0)
	s_setprio 1
	s_waitcnt lgkmcnt(0)
	v_mfma_f32_16x16x32_bf16 v[60:63], v[142:145], v[164:167], v[60:63]
	v_mfma_f32_16x16x32_bf16 v[56:59], v[150:153], v[164:167], v[56:59]
	v_mfma_f32_16x16x32_bf16 v[44:47], v[142:145], v[172:175], v[44:47]
	v_mfma_f32_16x16x32_bf16 v[40:43], v[150:153], v[172:175], v[40:43]
	v_mfma_f32_16x16x32_bf16 v[28:31], v[142:145], v[180:183], v[28:31]
	v_mfma_f32_16x16x32_bf16 v[24:27], v[150:153], v[180:183], v[24:27]
	v_mfma_f32_16x16x32_bf16 v[12:15], v[142:145], v[188:191], v[12:15]
	v_mfma_f32_16x16x32_bf16 v[8:11], v[150:153], v[188:191], v[8:11]
	v_mfma_f32_16x16x32_bf16 v[60:63], v[146:149], v[168:171], v[60:63]
	v_mfma_f32_16x16x32_bf16 v[56:59], v[154:157], v[168:171], v[56:59]
	v_mfma_f32_16x16x32_bf16 v[44:47], v[146:149], v[176:179], v[44:47]
	v_mfma_f32_16x16x32_bf16 v[40:43], v[154:157], v[176:179], v[40:43]
	v_mfma_f32_16x16x32_bf16 v[28:31], v[146:149], v[184:187], v[28:31]
	v_mfma_f32_16x16x32_bf16 v[24:27], v[154:157], v[184:187], v[24:27]
	v_mfma_f32_16x16x32_bf16 v[12:15], v[146:149], v[192:195], v[12:15]
	v_mfma_f32_16x16x32_bf16 v[8:11], v[154:157], v[192:195], v[8:11]
	s_setprio 0
	s_barrier
	s_add_u32 s68, s60, 0x80000
	s_addc_u32 s69, s61, 0
	s_add_i32 s55, s55, s41
	v_lshl_add_u64 v[142:143], s[68:69], 0, v[128:129]
	s_mov_b32 m0, s55
	s_nop 0
	global_load_lds_dwordx4 v[142:143], off
	v_lshl_add_u64 v[142:143], s[68:69], 0, v[136:137]
	s_add_i32 m0, s55, 0x2000
	s_nop 0
	global_load_lds_dwordx4 v[142:143], off
	s_waitcnt vmcnt(6)
	s_barrier
	s_setprio 1
	v_mfma_f32_16x16x32_bf16 v[52:55], v[196:199], v[164:167], v[52:55]
	v_mfma_f32_16x16x32_bf16 v[48:51], v[204:207], v[164:167], v[48:51]
	v_mfma_f32_16x16x32_bf16 v[36:39], v[196:199], v[172:175], v[36:39]
	v_mfma_f32_16x16x32_bf16 v[32:35], v[204:207], v[172:175], v[32:35]
	v_mfma_f32_16x16x32_bf16 v[20:23], v[196:199], v[180:183], v[20:23]
	v_mfma_f32_16x16x32_bf16 v[16:19], v[204:207], v[180:183], v[16:19]
	v_mfma_f32_16x16x32_bf16 v[4:7], v[196:199], v[188:191], v[4:7]
	v_mfma_f32_16x16x32_bf16 v[0:3], v[204:207], v[188:191], v[0:3]
	v_mfma_f32_16x16x32_bf16 v[52:55], v[200:203], v[168:171], v[52:55]
	v_mfma_f32_16x16x32_bf16 v[48:51], v[208:211], v[168:171], v[48:51]
	v_mfma_f32_16x16x32_bf16 v[36:39], v[200:203], v[176:179], v[36:39]
	v_mfma_f32_16x16x32_bf16 v[32:35], v[208:211], v[176:179], v[32:35]
	v_mfma_f32_16x16x32_bf16 v[20:23], v[200:203], v[184:187], v[20:23]
	v_mfma_f32_16x16x32_bf16 v[16:19], v[208:211], v[184:187], v[16:19]
	v_mfma_f32_16x16x32_bf16 v[4:7], v[200:203], v[192:195], v[4:7]
	v_mfma_f32_16x16x32_bf16 v[0:3], v[208:211], v[192:195], v[0:3]
	s_setprio 0
	s_add_i32 s55, 0, 0x18000
	v_add_u32_e32 v154, s55, v159
	s_barrier
	ds_read_b128 v[142:145], v154
	ds_read_b128 v[146:149], v154 offset:1024
	ds_read_b128 v[150:153], v154 offset:2048
	ds_read_b128 v[154:157], v154 offset:3072
	s_add_u32 s62, s62, 0x80000
	s_addc_u32 s63, s63, 0
	s_mov_b32 m0, s45
	v_lshl_add_u64 v[196:197], s[62:63], 0, v[132:133]
	ds_read_b128 v[164:167], v162 offset:32768
	ds_read_b128 v[168:171], v162 offset:33792
	ds_read_b128 v[172:175], v162 offset:34816
	ds_read_b128 v[176:179], v162 offset:35840
	ds_read_b128 v[180:183], v162 offset:36864
	ds_read_b128 v[184:187], v162 offset:37888
	ds_read_b128 v[188:191], v162 offset:38912
	ds_read_b128 v[192:195], v162 offset:39936
	global_load_lds_dwordx4 v[196:197], off
	v_lshl_add_u64 v[196:197], s[62:63], 0, v[134:135]
	s_mov_b32 m0, s46
	s_nop 0
	global_load_lds_dwordx4 v[196:197], off
	s_waitcnt lgkmcnt(8)
	s_barrier
	s_waitcnt lgkmcnt(0)
	s_setprio 1
	s_waitcnt lgkmcnt(0)
	v_mfma_f32_16x16x32_bf16 v[124:127], v[142:145], v[164:167], v[124:127]
	v_mfma_f32_16x16x32_bf16 v[120:123], v[150:153], v[164:167], v[120:123]
	v_mfma_f32_16x16x32_bf16 v[108:111], v[142:145], v[172:175], v[108:111]
	v_mfma_f32_16x16x32_bf16 v[104:107], v[150:153], v[172:175], v[104:107]
	v_mfma_f32_16x16x32_bf16 v[92:95], v[142:145], v[180:183], v[92:95]
	v_mfma_f32_16x16x32_bf16 v[88:91], v[150:153], v[180:183], v[88:91]
	v_mfma_f32_16x16x32_bf16 v[76:79], v[142:145], v[188:191], v[76:79]
	v_mfma_f32_16x16x32_bf16 v[72:75], v[150:153], v[188:191], v[72:75]
	v_mfma_f32_16x16x32_bf16 v[124:127], v[146:149], v[168:171], v[124:127]
	v_mfma_f32_16x16x32_bf16 v[120:123], v[154:157], v[168:171], v[120:123]
	v_mfma_f32_16x16x32_bf16 v[108:111], v[146:149], v[176:179], v[108:111]
	v_mfma_f32_16x16x32_bf16 v[104:107], v[154:157], v[176:179], v[104:107]
	v_mfma_f32_16x16x32_bf16 v[92:95], v[146:149], v[184:187], v[92:95]
	v_mfma_f32_16x16x32_bf16 v[88:91], v[154:157], v[184:187], v[88:91]
	v_mfma_f32_16x16x32_bf16 v[76:79], v[146:149], v[192:195], v[76:79]
	v_mfma_f32_16x16x32_bf16 v[72:75], v[154:157], v[192:195], v[72:75]
	s_setprio 0
	s_barrier
	s_add_i32 s57, 0, 0x1c000
	s_add_i32 s55, s55, s41
	v_add_u32_e32 v163, s57, v159
	v_lshl_add_u64 v[212:213], v[212:213], 0, s[8:9]
	s_mov_b32 m0, s55
	ds_read_b128 v[196:199], v163
	ds_read_b128 v[200:203], v163 offset:1024
	ds_read_b128 v[204:207], v163 offset:2048
	ds_read_b128 v[208:211], v163 offset:3072
	global_load_lds_dwordx4 v[212:213], off
	v_lshl_add_u64 v[212:213], v[214:215], 0, s[8:9]
	s_add_i32 m0, s55, 0x2000
	s_nop 0
	global_load_lds_dwordx4 v[212:213], off
	s_barrier
	s_waitcnt lgkmcnt(0)
	s_setprio 1
	s_waitcnt lgkmcnt(0)
	v_mfma_f32_16x16x32_bf16 v[116:119], v[196:199], v[164:167], v[116:119]
	v_mfma_f32_16x16x32_bf16 v[112:115], v[204:207], v[164:167], v[112:115]
	v_mfma_f32_16x16x32_bf16 v[100:103], v[196:199], v[172:175], v[100:103]
	v_mfma_f32_16x16x32_bf16 v[96:99], v[204:207], v[172:175], v[96:99]
	v_mfma_f32_16x16x32_bf16 v[84:87], v[196:199], v[180:183], v[84:87]
	v_mfma_f32_16x16x32_bf16 v[80:83], v[204:207], v[180:183], v[80:83]
	v_mfma_f32_16x16x32_bf16 v[68:71], v[196:199], v[188:191], v[68:71]
	v_mfma_f32_16x16x32_bf16 v[64:67], v[204:207], v[188:191], v[64:67]
	v_mfma_f32_16x16x32_bf16 v[116:119], v[200:203], v[168:171], v[116:119]
	v_mfma_f32_16x16x32_bf16 v[112:115], v[208:211], v[168:171], v[112:115]
	v_mfma_f32_16x16x32_bf16 v[100:103], v[200:203], v[176:179], v[100:103]
	v_mfma_f32_16x16x32_bf16 v[96:99], v[208:211], v[176:179], v[96:99]
	v_mfma_f32_16x16x32_bf16 v[84:87], v[200:203], v[184:187], v[84:87]
	v_mfma_f32_16x16x32_bf16 v[80:83], v[208:211], v[184:187], v[80:83]
	v_mfma_f32_16x16x32_bf16 v[68:71], v[200:203], v[192:195], v[68:71]
	v_mfma_f32_16x16x32_bf16 v[64:67], v[208:211], v[192:195], v[64:67]
	s_setprio 0
	s_mov_b32 m0, s33
	v_lshl_add_u64 v[212:213], v[216:217], 0, s[8:9]
	s_barrier
	ds_read_b128 v[164:167], v162 offset:49152
	ds_read_b128 v[168:171], v162 offset:50176
	ds_read_b128 v[172:175], v162 offset:51200
	ds_read_b128 v[176:179], v162 offset:52224
	ds_read_b128 v[180:183], v162 offset:53248
	ds_read_b128 v[184:187], v162 offset:54272
	ds_read_b128 v[188:191], v162 offset:55296
	ds_read_b128 v[192:195], v162 offset:56320
	global_load_lds_dwordx4 v[212:213], off
	v_lshl_add_u64 v[212:213], v[218:219], 0, s[8:9]
	s_mov_b32 m0, s47
	s_nop 0
	global_load_lds_dwordx4 v[212:213], off
	s_barrier
	s_waitcnt lgkmcnt(0)
	s_setprio 1
	s_waitcnt lgkmcnt(0)
	v_mfma_f32_16x16x32_bf16 v[60:63], v[142:145], v[164:167], v[60:63]
	v_mfma_f32_16x16x32_bf16 v[56:59], v[150:153], v[164:167], v[56:59]
	v_mfma_f32_16x16x32_bf16 v[44:47], v[142:145], v[172:175], v[44:47]
	v_mfma_f32_16x16x32_bf16 v[40:43], v[150:153], v[172:175], v[40:43]
	v_mfma_f32_16x16x32_bf16 v[28:31], v[142:145], v[180:183], v[28:31]
	v_mfma_f32_16x16x32_bf16 v[24:27], v[150:153], v[180:183], v[24:27]
	v_mfma_f32_16x16x32_bf16 v[12:15], v[142:145], v[188:191], v[12:15]
	v_mfma_f32_16x16x32_bf16 v[8:11], v[150:153], v[188:191], v[8:11]
	v_mfma_f32_16x16x32_bf16 v[60:63], v[146:149], v[168:171], v[60:63]
	v_mfma_f32_16x16x32_bf16 v[56:59], v[154:157], v[168:171], v[56:59]
	v_mfma_f32_16x16x32_bf16 v[44:47], v[146:149], v[176:179], v[44:47]
	v_mfma_f32_16x16x32_bf16 v[40:43], v[154:157], v[176:179], v[40:43]
	v_mfma_f32_16x16x32_bf16 v[28:31], v[146:149], v[184:187], v[28:31]
	v_mfma_f32_16x16x32_bf16 v[24:27], v[154:157], v[184:187], v[24:27]
	v_mfma_f32_16x16x32_bf16 v[12:15], v[146:149], v[192:195], v[12:15]
	v_mfma_f32_16x16x32_bf16 v[8:11], v[154:157], v[192:195], v[8:11]
	s_setprio 0
	s_barrier
	s_add_u32 s60, s60, 0x80080
	s_addc_u32 s61, s61, 0
	s_add_i32 s55, s57, s41
	v_lshl_add_u64 v[142:143], s[60:61], 0, v[128:129]
	s_mov_b32 m0, s55
	s_nop 0
	global_load_lds_dwordx4 v[142:143], off
	v_lshl_add_u64 v[142:143], s[60:61], 0, v[136:137]
	s_add_i32 m0, s55, 0x2000
	s_nop 0
	global_load_lds_dwordx4 v[142:143], off
	s_waitcnt vmcnt(6)
	s_barrier
	s_setprio 1
	v_mfma_f32_16x16x32_bf16 v[52:55], v[196:199], v[164:167], v[52:55]
	v_mfma_f32_16x16x32_bf16 v[48:51], v[204:207], v[164:167], v[48:51]
	v_mfma_f32_16x16x32_bf16 v[36:39], v[196:199], v[172:175], v[36:39]
	v_mfma_f32_16x16x32_bf16 v[32:35], v[204:207], v[172:175], v[32:35]
	v_mfma_f32_16x16x32_bf16 v[20:23], v[196:199], v[180:183], v[20:23]
	v_mfma_f32_16x16x32_bf16 v[16:19], v[204:207], v[180:183], v[16:19]
	v_mfma_f32_16x16x32_bf16 v[4:7], v[196:199], v[188:191], v[4:7]
	v_mfma_f32_16x16x32_bf16 v[0:3], v[204:207], v[188:191], v[0:3]
	v_mfma_f32_16x16x32_bf16 v[52:55], v[200:203], v[168:171], v[52:55]
	v_mfma_f32_16x16x32_bf16 v[48:51], v[208:211], v[168:171], v[48:51]
	v_mfma_f32_16x16x32_bf16 v[36:39], v[200:203], v[176:179], v[36:39]
	v_mfma_f32_16x16x32_bf16 v[32:35], v[208:211], v[176:179], v[32:35]
	v_mfma_f32_16x16x32_bf16 v[20:23], v[200:203], v[184:187], v[20:23]
	v_mfma_f32_16x16x32_bf16 v[16:19], v[208:211], v[184:187], v[16:19]
	v_mfma_f32_16x16x32_bf16 v[4:7], v[200:203], v[192:195], v[4:7]
	v_mfma_f32_16x16x32_bf16 v[0:3], v[208:211], v[192:195], v[0:3]
	s_setprio 0
	s_add_u32 vcc_lo, vcc_lo, 0x100
	s_addc_u32 vcc_hi, vcc_hi, 0
	s_add_u32 s53, s53, 0x100
	s_addc_u32 s54, s54, 0
	s_cmp_ge_i32 s56, s25
	s_mov_b32 s55, s56
	s_barrier
	s_cbranch_scc0 .LBB0_1239
	v_lshl_add_u32 v150, s26, 8, v158
	v_lshl_or_b32 v148, s24, 8, v161
	v_or_b32_e32 v146, 16, v150
	v_or_b32_e32 v144, 32, v150
	v_or_b32_e32 v142, 48, v150
	s_mov_b64 s[24:25], -1
	s_cmp_eq_u32 s26, 32
	v_ashrrev_i32_e32 v151, 31, v150
	v_ashrrev_i32_e32 v149, 31, v148
	v_ashrrev_i32_e32 v147, 31, v146
	v_ashrrev_i32_e32 v145, 31, v144
	v_ashrrev_i32_e32 v143, 31, v142
	s_cbranch_scc1 .LBB0_1242
	v_lshlrev_b64 v[154:155], 13, v[150:151]
	v_lshlrev_b64 v[156:157], 1, v[148:149]
	v_lshlrev_b64 v[152:153], 2, v[148:149]
	v_lshl_add_u64 v[170:171], s[0:1], 0, v[154:155]
	v_lshl_add_u64 v[170:171], v[170:171], 0, v[156:157]
	v_lshl_add_u64 v[168:169], s[4:5], 0, v[154:155]
	v_lshl_add_u64 v[168:169], v[168:169], 0, v[152:153]
	v_mov_b32_e32 v166, v170
	v_mov_b32_e32 v167, v171
	global_load_dwordx2 v[172:173], v[166:167], off offset:0
	global_load_dwordx2 v[174:175], v[166:167], off offset:8
	global_load_dwordx2 v[176:177], v[166:167], off offset:256
	global_load_dwordx2 v[178:179], v[166:167], off offset:264
	s_mov_b64 s[24:25], 0x20000
	v_lshl_add_u64 v[166:167], v[170:171], 0, s[24:25]
	global_load_dwordx2 v[180:181], v[166:167], off offset:0
	global_load_dwordx2 v[182:183], v[166:167], off offset:8
	global_load_dwordx2 v[184:185], v[166:167], off offset:256
	global_load_dwordx2 v[186:187], v[166:167], off offset:264
	s_mov_b64 s[24:25], 0x40000
	v_lshl_add_u64 v[166:167], v[170:171], 0, s[24:25]
	global_load_dwordx2 v[188:189], v[166:167], off offset:0
	global_load_dwordx2 v[190:191], v[166:167], off offset:8
	global_load_dwordx2 v[192:193], v[166:167], off offset:256
	global_load_dwordx2 v[194:195], v[166:167], off offset:264
	s_mov_b64 s[24:25], 0x60000
	v_lshl_add_u64 v[166:167], v[170:171], 0, s[24:25]
	global_load_dwordx2 v[196:197], v[166:167], off offset:0
	global_load_dwordx2 v[198:199], v[166:167], off offset:8
	global_load_dwordx2 v[200:201], v[166:167], off offset:256
	global_load_dwordx2 v[202:203], v[166:167], off offset:264
	v_lshl_add_u64 v[166:167], v[170:171], 0, s[10:11]
	global_load_dwordx2 v[204:205], v[166:167], off offset:0
	global_load_dwordx2 v[206:207], v[166:167], off offset:8
	global_load_dwordx2 v[208:209], v[166:167], off offset:256
	global_load_dwordx2 v[210:211], v[166:167], off offset:264
	v_lshl_add_u64 v[166:167], v[170:171], 0, s[12:13]
	global_load_dwordx2 v[212:213], v[166:167], off offset:0
	global_load_dwordx2 v[214:215], v[166:167], off offset:8
	global_load_dwordx2 v[216:217], v[166:167], off offset:256
	global_load_dwordx2 v[218:219], v[166:167], off offset:264
	v_lshl_add_u64 v[166:167], v[170:171], 0, s[14:15]
	global_load_dwordx2 v[220:221], v[166:167], off offset:0
	global_load_dwordx2 v[222:223], v[166:167], off offset:8
	global_load_dwordx2 v[224:225], v[166:167], off offset:256
	global_load_dwordx2 v[226:227], v[166:167], off offset:264
	v_lshl_add_u64 v[166:167], v[170:171], 0, s[36:37]
	global_load_dwordx2 v[228:229], v[166:167], off offset:0
	global_load_dwordx2 v[232:233], v[166:167], off offset:8
	global_load_dwordx2 v[234:235], v[166:167], off offset:256
	global_load_dwordx2 v[236:237], v[166:167], off offset:264
	v_mov_b32_e32 v244, v168
	v_mov_b32_e32 v245, v169
	s_waitcnt vmcnt(31)
	v_lshlrev_b32_e32 v164, 16, v172
	v_and_b32_e32 v165, 0xffff0000, v172
	v_lshlrev_b32_e32 v166, 16, v173
	v_and_b32_e32 v167, 0xffff0000, v173
	v_pk_mul_f32 v[124:125], v[124:125], v[164:165]
	v_pk_mul_f32 v[126:127], v[126:127], v[166:167]
	global_store_dwordx4 v[244:245], v[124:127], off offset:0
	s_waitcnt vmcnt(31)
	v_lshlrev_b32_e32 v240, 16, v174
	v_and_b32_e32 v241, 0xffff0000, v174
	v_lshlrev_b32_e32 v242, 16, v175
	v_and_b32_e32 v243, 0xffff0000, v175
	v_pk_mul_f32 v[120:121], v[120:121], v[240:241]
	v_pk_mul_f32 v[122:123], v[122:123], v[242:243]
	global_store_dwordx4 v[244:245], v[120:123], off offset:16
	s_waitcnt vmcnt(31)
	v_lshlrev_b32_e32 v164, 16, v176
	v_and_b32_e32 v165, 0xffff0000, v176
	v_lshlrev_b32_e32 v166, 16, v177
	v_and_b32_e32 v167, 0xffff0000, v177
	v_pk_mul_f32 v[116:117], v[116:117], v[164:165]
	v_pk_mul_f32 v[118:119], v[118:119], v[166:167]
	global_store_dwordx4 v[244:245], v[116:119], off offset:512
	s_waitcnt vmcnt(31)
	v_lshlrev_b32_e32 v240, 16, v178
	v_and_b32_e32 v241, 0xffff0000, v178
	v_lshlrev_b32_e32 v242, 16, v179
	v_and_b32_e32 v243, 0xffff0000, v179
	v_pk_mul_f32 v[112:113], v[112:113], v[240:241]
	v_pk_mul_f32 v[114:115], v[114:115], v[242:243]
	global_store_dwordx4 v[244:245], v[112:115], off offset:528
	s_mov_b64 s[24:25], 0x20000
	v_lshl_add_u64 v[244:245], v[168:169], 0, s[24:25]
	s_waitcnt vmcnt(31)
	v_lshlrev_b32_e32 v164, 16, v180
	v_and_b32_e32 v165, 0xffff0000, v180
	v_lshlrev_b32_e32 v166, 16, v181
	v_and_b32_e32 v167, 0xffff0000, v181
	v_pk_mul_f32 v[108:109], v[108:109], v[164:165]
	v_pk_mul_f32 v[110:111], v[110:111], v[166:167]
	global_store_dwordx4 v[244:245], v[108:111], off offset:0
	s_waitcnt vmcnt(31)
	v_lshlrev_b32_e32 v240, 16, v182
	v_and_b32_e32 v241, 0xffff0000, v182
	v_lshlrev_b32_e32 v242, 16, v183
	v_and_b32_e32 v243, 0xffff0000, v183
	v_pk_mul_f32 v[104:105], v[104:105], v[240:241]
	v_pk_mul_f32 v[106:107], v[106:107], v[242:243]
	global_store_dwordx4 v[244:245], v[104:107], off offset:16
	s_waitcnt vmcnt(31)
	v_lshlrev_b32_e32 v164, 16, v184
	v_and_b32_e32 v165, 0xffff0000, v184
	v_lshlrev_b32_e32 v166, 16, v185
	v_and_b32_e32 v167, 0xffff0000, v185
	v_pk_mul_f32 v[100:101], v[100:101], v[164:165]
	v_pk_mul_f32 v[102:103], v[102:103], v[166:167]
	global_store_dwordx4 v[244:245], v[100:103], off offset:512
	s_waitcnt vmcnt(31)
	v_lshlrev_b32_e32 v240, 16, v186
	v_and_b32_e32 v241, 0xffff0000, v186
	v_lshlrev_b32_e32 v242, 16, v187
	v_and_b32_e32 v243, 0xffff0000, v187
	v_pk_mul_f32 v[96:97], v[96:97], v[240:241]
	v_pk_mul_f32 v[98:99], v[98:99], v[242:243]
	global_store_dwordx4 v[244:245], v[96:99], off offset:528
	s_mov_b64 s[24:25], 0x40000
	v_lshl_add_u64 v[244:245], v[168:169], 0, s[24:25]
	s_waitcnt vmcnt(31)
	v_lshlrev_b32_e32 v164, 16, v188
	v_and_b32_e32 v165, 0xffff0000, v188
	v_lshlrev_b32_e32 v166, 16, v189
	v_and_b32_e32 v167, 0xffff0000, v189
	v_pk_mul_f32 v[92:93], v[92:93], v[164:165]
	v_pk_mul_f32 v[94:95], v[94:95], v[166:167]
	global_store_dwordx4 v[244:245], v[92:95], off offset:0
	s_waitcnt vmcnt(31)
	v_lshlrev_b32_e32 v240, 16, v190
	v_and_b32_e32 v241, 0xffff0000, v190
	v_lshlrev_b32_e32 v242, 16, v191
	v_and_b32_e32 v243, 0xffff0000, v191
	v_pk_mul_f32 v[88:89], v[88:89], v[240:241]
	v_pk_mul_f32 v[90:91], v[90:91], v[242:243]
	global_store_dwordx4 v[244:245], v[88:91], off offset:16
	s_waitcnt vmcnt(31)
	v_lshlrev_b32_e32 v164, 16, v192
	v_and_b32_e32 v165, 0xffff0000, v192
	v_lshlrev_b32_e32 v166, 16, v193
	v_and_b32_e32 v167, 0xffff0000, v193
	v_pk_mul_f32 v[84:85], v[84:85], v[164:165]
	v_pk_mul_f32 v[86:87], v[86:87], v[166:167]
	global_store_dwordx4 v[244:245], v[84:87], off offset:512
	s_waitcnt vmcnt(31)
	v_lshlrev_b32_e32 v240, 16, v194
	v_and_b32_e32 v241, 0xffff0000, v194
	v_lshlrev_b32_e32 v242, 16, v195
	v_and_b32_e32 v243, 0xffff0000, v195
	v_pk_mul_f32 v[80:81], v[80:81], v[240:241]
	v_pk_mul_f32 v[82:83], v[82:83], v[242:243]
	global_store_dwordx4 v[244:245], v[80:83], off offset:528
	s_mov_b64 s[24:25], 0x60000
	v_lshl_add_u64 v[244:245], v[168:169], 0, s[24:25]
	s_waitcnt vmcnt(31)
	v_lshlrev_b32_e32 v164, 16, v196
	v_and_b32_e32 v165, 0xffff0000, v196
	v_lshlrev_b32_e32 v166, 16, v197
	v_and_b32_e32 v167, 0xffff0000, v197
	v_pk_mul_f32 v[76:77], v[76:77], v[164:165]
	v_pk_mul_f32 v[78:79], v[78:79], v[166:167]
	global_store_dwordx4 v[244:245], v[76:79], off offset:0
	s_waitcnt vmcnt(31)
	v_lshlrev_b32_e32 v240, 16, v198
	v_and_b32_e32 v241, 0xffff0000, v198
	v_lshlrev_b32_e32 v242, 16, v199
	v_and_b32_e32 v243, 0xffff0000, v199
	v_pk_mul_f32 v[72:73], v[72:73], v[240:241]
	v_pk_mul_f32 v[74:75], v[74:75], v[242:243]
	global_store_dwordx4 v[244:245], v[72:75], off offset:16
	s_waitcnt vmcnt(31)
	v_lshlrev_b32_e32 v164, 16, v200
	v_and_b32_e32 v165, 0xffff0000, v200
	v_lshlrev_b32_e32 v166, 16, v201
	v_and_b32_e32 v167, 0xffff0000, v201
	v_pk_mul_f32 v[68:69], v[68:69], v[164:165]
	v_pk_mul_f32 v[70:71], v[70:71], v[166:167]
	global_store_dwordx4 v[244:245], v[68:71], off offset:512
	s_waitcnt vmcnt(31)
	v_lshlrev_b32_e32 v240, 16, v202
	v_and_b32_e32 v241, 0xffff0000, v202
	v_lshlrev_b32_e32 v242, 16, v203
	v_and_b32_e32 v243, 0xffff0000, v203
	v_pk_mul_f32 v[64:65], v[64:65], v[240:241]
	v_pk_mul_f32 v[66:67], v[66:67], v[242:243]
	global_store_dwordx4 v[244:245], v[64:67], off offset:528
	v_lshl_add_u64 v[244:245], v[168:169], 0, s[10:11]
	s_waitcnt vmcnt(31)
	v_lshlrev_b32_e32 v164, 16, v204
	v_and_b32_e32 v165, 0xffff0000, v204
	v_lshlrev_b32_e32 v166, 16, v205
	v_and_b32_e32 v167, 0xffff0000, v205
	v_pk_mul_f32 v[60:61], v[60:61], v[164:165]
	v_pk_mul_f32 v[62:63], v[62:63], v[166:167]
	global_store_dwordx4 v[244:245], v[60:63], off offset:0
	s_waitcnt vmcnt(31)
	v_lshlrev_b32_e32 v240, 16, v206
	v_and_b32_e32 v241, 0xffff0000, v206
	v_lshlrev_b32_e32 v242, 16, v207
	v_and_b32_e32 v243, 0xffff0000, v207
	v_pk_mul_f32 v[56:57], v[56:57], v[240:241]
	v_pk_mul_f32 v[58:59], v[58:59], v[242:243]
	global_store_dwordx4 v[244:245], v[56:59], off offset:16
	s_waitcnt vmcnt(31)
	v_lshlrev_b32_e32 v164, 16, v208
	v_and_b32_e32 v165, 0xffff0000, v208
	v_lshlrev_b32_e32 v166, 16, v209
	v_and_b32_e32 v167, 0xffff0000, v209
	v_pk_mul_f32 v[52:53], v[52:53], v[164:165]
	v_pk_mul_f32 v[54:55], v[54:55], v[166:167]
	global_store_dwordx4 v[244:245], v[52:55], off offset:512
	s_waitcnt vmcnt(31)
	v_lshlrev_b32_e32 v240, 16, v210
	v_and_b32_e32 v241, 0xffff0000, v210
	v_lshlrev_b32_e32 v242, 16, v211
	v_and_b32_e32 v243, 0xffff0000, v211
	v_pk_mul_f32 v[48:49], v[48:49], v[240:241]
	v_pk_mul_f32 v[50:51], v[50:51], v[242:243]
	global_store_dwordx4 v[244:245], v[48:51], off offset:528
	v_lshl_add_u64 v[244:245], v[168:169], 0, s[12:13]
	s_waitcnt vmcnt(31)
	v_lshlrev_b32_e32 v164, 16, v212
	v_and_b32_e32 v165, 0xffff0000, v212
	v_lshlrev_b32_e32 v166, 16, v213
	v_and_b32_e32 v167, 0xffff0000, v213
	v_pk_mul_f32 v[44:45], v[44:45], v[164:165]
	v_pk_mul_f32 v[46:47], v[46:47], v[166:167]
	global_store_dwordx4 v[244:245], v[44:47], off offset:0
	s_waitcnt vmcnt(31)
	v_lshlrev_b32_e32 v240, 16, v214
	v_and_b32_e32 v241, 0xffff0000, v214
	v_lshlrev_b32_e32 v242, 16, v215
	v_and_b32_e32 v243, 0xffff0000, v215
	v_pk_mul_f32 v[40:41], v[40:41], v[240:241]
	v_pk_mul_f32 v[42:43], v[42:43], v[242:243]
	global_store_dwordx4 v[244:245], v[40:43], off offset:16
	s_waitcnt vmcnt(31)
	v_lshlrev_b32_e32 v164, 16, v216
	v_and_b32_e32 v165, 0xffff0000, v216
	v_lshlrev_b32_e32 v166, 16, v217
	v_and_b32_e32 v167, 0xffff0000, v217
	v_pk_mul_f32 v[36:37], v[36:37], v[164:165]
	v_pk_mul_f32 v[38:39], v[38:39], v[166:167]
	global_store_dwordx4 v[244:245], v[36:39], off offset:512
	s_waitcnt vmcnt(31)
	v_lshlrev_b32_e32 v240, 16, v218
	v_and_b32_e32 v241, 0xffff0000, v218
	v_lshlrev_b32_e32 v242, 16, v219
	v_and_b32_e32 v243, 0xffff0000, v219
	v_pk_mul_f32 v[32:33], v[32:33], v[240:241]
	v_pk_mul_f32 v[34:35], v[34:35], v[242:243]
	global_store_dwordx4 v[244:245], v[32:35], off offset:528
	v_lshl_add_u64 v[244:245], v[168:169], 0, s[14:15]
	s_waitcnt vmcnt(31)
	v_lshlrev_b32_e32 v164, 16, v220
	v_and_b32_e32 v165, 0xffff0000, v220
	v_lshlrev_b32_e32 v166, 16, v221
	v_and_b32_e32 v167, 0xffff0000, v221
	v_pk_mul_f32 v[28:29], v[28:29], v[164:165]
	v_pk_mul_f32 v[30:31], v[30:31], v[166:167]
	global_store_dwordx4 v[244:245], v[28:31], off offset:0
	s_waitcnt vmcnt(31)
	v_lshlrev_b32_e32 v240, 16, v222
	v_and_b32_e32 v241, 0xffff0000, v222
	v_lshlrev_b32_e32 v242, 16, v223
	v_and_b32_e32 v243, 0xffff0000, v223
	v_pk_mul_f32 v[24:25], v[24:25], v[240:241]
	v_pk_mul_f32 v[26:27], v[26:27], v[242:243]
	global_store_dwordx4 v[244:245], v[24:27], off offset:16
	s_waitcnt vmcnt(31)
	v_lshlrev_b32_e32 v164, 16, v224
	v_and_b32_e32 v165, 0xffff0000, v224
	v_lshlrev_b32_e32 v166, 16, v225
	v_and_b32_e32 v167, 0xffff0000, v225
	v_pk_mul_f32 v[20:21], v[20:21], v[164:165]
	v_pk_mul_f32 v[22:23], v[22:23], v[166:167]
	global_store_dwordx4 v[244:245], v[20:23], off offset:512
	s_waitcnt vmcnt(31)
	v_lshlrev_b32_e32 v240, 16, v226
	v_and_b32_e32 v241, 0xffff0000, v226
	v_lshlrev_b32_e32 v242, 16, v227
	v_and_b32_e32 v243, 0xffff0000, v227
	v_pk_mul_f32 v[16:17], v[16:17], v[240:241]
	v_pk_mul_f32 v[18:19], v[18:19], v[242:243]
	global_store_dwordx4 v[244:245], v[16:19], off offset:528
	v_lshl_add_u64 v[244:245], v[168:169], 0, s[36:37]
	s_waitcnt vmcnt(31)
	v_lshlrev_b32_e32 v164, 16, v228
	v_and_b32_e32 v165, 0xffff0000, v228
	v_lshlrev_b32_e32 v166, 16, v229
	v_and_b32_e32 v167, 0xffff0000, v229
	v_pk_mul_f32 v[12:13], v[12:13], v[164:165]
	v_pk_mul_f32 v[14:15], v[14:15], v[166:167]
	global_store_dwordx4 v[244:245], v[12:15], off offset:0
	s_waitcnt vmcnt(31)
	v_lshlrev_b32_e32 v240, 16, v232
	v_and_b32_e32 v241, 0xffff0000, v232
	v_lshlrev_b32_e32 v242, 16, v233
	v_and_b32_e32 v243, 0xffff0000, v233
	v_pk_mul_f32 v[8:9], v[8:9], v[240:241]
	v_pk_mul_f32 v[10:11], v[10:11], v[242:243]
	global_store_dwordx4 v[244:245], v[8:11], off offset:16
	s_waitcnt vmcnt(31)
	v_lshlrev_b32_e32 v164, 16, v234
	v_and_b32_e32 v165, 0xffff0000, v234
	v_lshlrev_b32_e32 v166, 16, v235
	v_and_b32_e32 v167, 0xffff0000, v235
	v_pk_mul_f32 v[4:5], v[4:5], v[164:165]
	v_pk_mul_f32 v[6:7], v[6:7], v[166:167]
	global_store_dwordx4 v[244:245], v[4:7], off offset:512
	s_waitcnt vmcnt(31)
	v_lshlrev_b32_e32 v240, 16, v236
	v_and_b32_e32 v241, 0xffff0000, v236
	v_lshlrev_b32_e32 v242, 16, v237
	v_and_b32_e32 v243, 0xffff0000, v237
	v_pk_mul_f32 v[0:1], v[0:1], v[240:241]
	v_pk_mul_f32 v[2:3], v[2:3], v[242:243]
	global_store_dwordx4 v[244:245], v[0:3], off offset:528
	s_mov_b64 s[24:25], 0
.LBB0_1242:
	s_andn2_b64 vcc, exec, s[24:25]
	s_cbranch_vccnz .LBB0_1232
	s_ashr_i32 s24, s52, 10
	s_ashr_i32 s25, s24, 31
	s_lshl_b64 s[24:25], s[24:25], 21
	s_add_u32 s24, s42, s24
	s_addc_u32 s25, s43, s25
	s_sub_u32 s24, s24, 0x4000000
	s_subb_u32 s25, s25, 0
	v_lshlrev_b64 v[154:155], 13, v[150:151]
	v_lshlrev_b64 v[156:157], 1, v[148:149]
	v_lshlrev_b64 v[152:153], 2, v[148:149]
	v_lshl_add_u64 v[170:171], s[0:1], 0, v[154:155]
	v_lshl_add_u64 v[170:171], v[170:171], 0, v[156:157]
	v_lshl_add_u64 v[168:169], s[24:25], 0, v[154:155]
	v_lshl_add_u64 v[168:169], v[168:169], 0, v[152:153]
	v_mov_b32_e32 v166, v170
	v_mov_b32_e32 v167, v171
	global_load_dwordx2 v[172:173], v[166:167], off offset:0
	global_load_dwordx2 v[174:175], v[166:167], off offset:8
	global_load_dwordx2 v[176:177], v[166:167], off offset:256
	global_load_dwordx2 v[178:179], v[166:167], off offset:264
	s_mov_b64 vcc, 0x20000
	v_lshl_add_u64 v[166:167], v[170:171], 0, vcc
	global_load_dwordx2 v[180:181], v[166:167], off offset:0
	global_load_dwordx2 v[182:183], v[166:167], off offset:8
	global_load_dwordx2 v[184:185], v[166:167], off offset:256
	global_load_dwordx2 v[186:187], v[166:167], off offset:264
	s_mov_b64 vcc, 0x40000
	v_lshl_add_u64 v[166:167], v[170:171], 0, vcc
	global_load_dwordx2 v[188:189], v[166:167], off offset:0
	global_load_dwordx2 v[190:191], v[166:167], off offset:8
	global_load_dwordx2 v[192:193], v[166:167], off offset:256
	global_load_dwordx2 v[194:195], v[166:167], off offset:264
	s_mov_b64 vcc, 0x60000
	v_lshl_add_u64 v[166:167], v[170:171], 0, vcc
	global_load_dwordx2 v[196:197], v[166:167], off offset:0
	global_load_dwordx2 v[198:199], v[166:167], off offset:8
	global_load_dwordx2 v[200:201], v[166:167], off offset:256
	global_load_dwordx2 v[202:203], v[166:167], off offset:264
	s_mov_b64 vcc, 0x100000
	v_lshl_add_u64 v[166:167], v[170:171], 0, vcc
	global_load_dwordx2 v[204:205], v[166:167], off offset:0
	global_load_dwordx2 v[206:207], v[166:167], off offset:8
	global_load_dwordx2 v[208:209], v[166:167], off offset:256
	global_load_dwordx2 v[210:211], v[166:167], off offset:264
	s_mov_b64 vcc, 0x120000
	v_lshl_add_u64 v[166:167], v[170:171], 0, vcc
	global_load_dwordx2 v[212:213], v[166:167], off offset:0
	global_load_dwordx2 v[214:215], v[166:167], off offset:8
	global_load_dwordx2 v[216:217], v[166:167], off offset:256
	global_load_dwordx2 v[218:219], v[166:167], off offset:264
	s_mov_b64 vcc, 0x140000
	v_lshl_add_u64 v[166:167], v[170:171], 0, vcc
	global_load_dwordx2 v[220:221], v[166:167], off offset:0
	global_load_dwordx2 v[222:223], v[166:167], off offset:8
	global_load_dwordx2 v[224:225], v[166:167], off offset:256
	global_load_dwordx2 v[226:227], v[166:167], off offset:264
	s_mov_b64 vcc, 0x160000
	v_lshl_add_u64 v[166:167], v[170:171], 0, vcc
	global_load_dwordx2 v[228:229], v[166:167], off offset:0
	global_load_dwordx2 v[232:233], v[166:167], off offset:8
	global_load_dwordx2 v[234:235], v[166:167], off offset:256
	global_load_dwordx2 v[236:237], v[166:167], off offset:264
	v_mov_b32_e32 v244, v168
	v_mov_b32_e32 v245, v169
	s_waitcnt vmcnt(31)
	v_lshlrev_b32_e32 v164, 16, v172
	v_and_b32_e32 v165, 0xffff0000, v172
	v_lshlrev_b32_e32 v166, 16, v173
	v_and_b32_e32 v167, 0xffff0000, v173
	v_pk_mul_f32 v[124:125], v[124:125], v[164:165]
	v_pk_mul_f32 v[126:127], v[126:127], v[166:167]
	global_store_dwordx4 v[244:245], v[124:127], off offset:0
	s_waitcnt vmcnt(31)
	v_lshlrev_b32_e32 v240, 16, v174
	v_and_b32_e32 v241, 0xffff0000, v174
	v_lshlrev_b32_e32 v242, 16, v175
	v_and_b32_e32 v243, 0xffff0000, v175
	v_pk_mul_f32 v[120:121], v[120:121], v[240:241]
	v_pk_mul_f32 v[122:123], v[122:123], v[242:243]
	global_store_dwordx4 v[244:245], v[120:123], off offset:16
	s_waitcnt vmcnt(31)
	v_lshlrev_b32_e32 v164, 16, v176
	v_and_b32_e32 v165, 0xffff0000, v176
	v_lshlrev_b32_e32 v166, 16, v177
	v_and_b32_e32 v167, 0xffff0000, v177
	v_pk_mul_f32 v[116:117], v[116:117], v[164:165]
	v_pk_mul_f32 v[118:119], v[118:119], v[166:167]
	global_store_dwordx4 v[244:245], v[116:119], off offset:512
	s_waitcnt vmcnt(31)
	v_lshlrev_b32_e32 v240, 16, v178
	v_and_b32_e32 v241, 0xffff0000, v178
	v_lshlrev_b32_e32 v242, 16, v179
	v_and_b32_e32 v243, 0xffff0000, v179
	v_pk_mul_f32 v[112:113], v[112:113], v[240:241]
	v_pk_mul_f32 v[114:115], v[114:115], v[242:243]
	global_store_dwordx4 v[244:245], v[112:115], off offset:528
	s_mov_b64 vcc, 0x20000
	v_lshl_add_u64 v[244:245], v[168:169], 0, vcc
	s_waitcnt vmcnt(31)
	v_lshlrev_b32_e32 v164, 16, v180
	v_and_b32_e32 v165, 0xffff0000, v180
	v_lshlrev_b32_e32 v166, 16, v181
	v_and_b32_e32 v167, 0xffff0000, v181
	v_pk_mul_f32 v[108:109], v[108:109], v[164:165]
	v_pk_mul_f32 v[110:111], v[110:111], v[166:167]
	global_store_dwordx4 v[244:245], v[108:111], off offset:0
	s_waitcnt vmcnt(31)
	v_lshlrev_b32_e32 v240, 16, v182
	v_and_b32_e32 v241, 0xffff0000, v182
	v_lshlrev_b32_e32 v242, 16, v183
	v_and_b32_e32 v243, 0xffff0000, v183
	v_pk_mul_f32 v[104:105], v[104:105], v[240:241]
	v_pk_mul_f32 v[106:107], v[106:107], v[242:243]
	global_store_dwordx4 v[244:245], v[104:107], off offset:16
	s_waitcnt vmcnt(31)
	v_lshlrev_b32_e32 v164, 16, v184
	v_and_b32_e32 v165, 0xffff0000, v184
	v_lshlrev_b32_e32 v166, 16, v185
	v_and_b32_e32 v167, 0xffff0000, v185
	v_pk_mul_f32 v[100:101], v[100:101], v[164:165]
	v_pk_mul_f32 v[102:103], v[102:103], v[166:167]
	global_store_dwordx4 v[244:245], v[100:103], off offset:512
	s_waitcnt vmcnt(31)
	v_lshlrev_b32_e32 v240, 16, v186
	v_and_b32_e32 v241, 0xffff0000, v186
	v_lshlrev_b32_e32 v242, 16, v187
	v_and_b32_e32 v243, 0xffff0000, v187
	v_pk_mul_f32 v[96:97], v[96:97], v[240:241]
	v_pk_mul_f32 v[98:99], v[98:99], v[242:243]
	global_store_dwordx4 v[244:245], v[96:99], off offset:528
	s_mov_b64 vcc, 0x40000
	v_lshl_add_u64 v[244:245], v[168:169], 0, vcc
	s_waitcnt vmcnt(31)
	v_lshlrev_b32_e32 v164, 16, v188
	v_and_b32_e32 v165, 0xffff0000, v188
	v_lshlrev_b32_e32 v166, 16, v189
	v_and_b32_e32 v167, 0xffff0000, v189
	v_pk_mul_f32 v[92:93], v[92:93], v[164:165]
	v_pk_mul_f32 v[94:95], v[94:95], v[166:167]
	global_store_dwordx4 v[244:245], v[92:95], off offset:0
	s_waitcnt vmcnt(31)
	v_lshlrev_b32_e32 v240, 16, v190
	v_and_b32_e32 v241, 0xffff0000, v190
	v_lshlrev_b32_e32 v242, 16, v191
	v_and_b32_e32 v243, 0xffff0000, v191
	v_pk_mul_f32 v[88:89], v[88:89], v[240:241]
	v_pk_mul_f32 v[90:91], v[90:91], v[242:243]
	global_store_dwordx4 v[244:245], v[88:91], off offset:16
	s_waitcnt vmcnt(31)
	v_lshlrev_b32_e32 v164, 16, v192
	v_and_b32_e32 v165, 0xffff0000, v192
	v_lshlrev_b32_e32 v166, 16, v193
	v_and_b32_e32 v167, 0xffff0000, v193
	v_pk_mul_f32 v[84:85], v[84:85], v[164:165]
	v_pk_mul_f32 v[86:87], v[86:87], v[166:167]
	global_store_dwordx4 v[244:245], v[84:87], off offset:512
	s_waitcnt vmcnt(31)
	v_lshlrev_b32_e32 v240, 16, v194
	v_and_b32_e32 v241, 0xffff0000, v194
	v_lshlrev_b32_e32 v242, 16, v195
	v_and_b32_e32 v243, 0xffff0000, v195
	v_pk_mul_f32 v[80:81], v[80:81], v[240:241]
	v_pk_mul_f32 v[82:83], v[82:83], v[242:243]
	global_store_dwordx4 v[244:245], v[80:83], off offset:528
	s_mov_b64 vcc, 0x60000
	v_lshl_add_u64 v[244:245], v[168:169], 0, vcc
	s_waitcnt vmcnt(31)
	v_lshlrev_b32_e32 v164, 16, v196
	v_and_b32_e32 v165, 0xffff0000, v196
	v_lshlrev_b32_e32 v166, 16, v197
	v_and_b32_e32 v167, 0xffff0000, v197
	v_pk_mul_f32 v[76:77], v[76:77], v[164:165]
	v_pk_mul_f32 v[78:79], v[78:79], v[166:167]
	global_store_dwordx4 v[244:245], v[76:79], off offset:0
	s_waitcnt vmcnt(31)
	v_lshlrev_b32_e32 v240, 16, v198
	v_and_b32_e32 v241, 0xffff0000, v198
	v_lshlrev_b32_e32 v242, 16, v199
	v_and_b32_e32 v243, 0xffff0000, v199
	v_pk_mul_f32 v[72:73], v[72:73], v[240:241]
	v_pk_mul_f32 v[74:75], v[74:75], v[242:243]
	global_store_dwordx4 v[244:245], v[72:75], off offset:16
	s_waitcnt vmcnt(31)
	v_lshlrev_b32_e32 v164, 16, v200
	v_and_b32_e32 v165, 0xffff0000, v200
	v_lshlrev_b32_e32 v166, 16, v201
	v_and_b32_e32 v167, 0xffff0000, v201
	v_pk_mul_f32 v[68:69], v[68:69], v[164:165]
	v_pk_mul_f32 v[70:71], v[70:71], v[166:167]
	global_store_dwordx4 v[244:245], v[68:71], off offset:512
	s_waitcnt vmcnt(31)
	v_lshlrev_b32_e32 v240, 16, v202
	v_and_b32_e32 v241, 0xffff0000, v202
	v_lshlrev_b32_e32 v242, 16, v203
	v_and_b32_e32 v243, 0xffff0000, v203
	v_pk_mul_f32 v[64:65], v[64:65], v[240:241]
	v_pk_mul_f32 v[66:67], v[66:67], v[242:243]
	global_store_dwordx4 v[244:245], v[64:67], off offset:528
	s_mov_b64 vcc, 0x100000
	v_lshl_add_u64 v[244:245], v[168:169], 0, vcc
	s_waitcnt vmcnt(31)
	v_lshlrev_b32_e32 v164, 16, v204
	v_and_b32_e32 v165, 0xffff0000, v204
	v_lshlrev_b32_e32 v166, 16, v205
	v_and_b32_e32 v167, 0xffff0000, v205
	v_pk_mul_f32 v[60:61], v[60:61], v[164:165]
	v_pk_mul_f32 v[62:63], v[62:63], v[166:167]
	global_store_dwordx4 v[244:245], v[60:63], off offset:0
	s_waitcnt vmcnt(31)
	v_lshlrev_b32_e32 v240, 16, v206
	v_and_b32_e32 v241, 0xffff0000, v206
	v_lshlrev_b32_e32 v242, 16, v207
	v_and_b32_e32 v243, 0xffff0000, v207
	v_pk_mul_f32 v[56:57], v[56:57], v[240:241]
	v_pk_mul_f32 v[58:59], v[58:59], v[242:243]
	global_store_dwordx4 v[244:245], v[56:59], off offset:16
	s_waitcnt vmcnt(31)
	v_lshlrev_b32_e32 v164, 16, v208
	v_and_b32_e32 v165, 0xffff0000, v208
	v_lshlrev_b32_e32 v166, 16, v209
	v_and_b32_e32 v167, 0xffff0000, v209
	v_pk_mul_f32 v[52:53], v[52:53], v[164:165]
	v_pk_mul_f32 v[54:55], v[54:55], v[166:167]
	global_store_dwordx4 v[244:245], v[52:55], off offset:512
	s_waitcnt vmcnt(31)
	v_lshlrev_b32_e32 v240, 16, v210
	v_and_b32_e32 v241, 0xffff0000, v210
	v_lshlrev_b32_e32 v242, 16, v211
	v_and_b32_e32 v243, 0xffff0000, v211
	v_pk_mul_f32 v[48:49], v[48:49], v[240:241]
	v_pk_mul_f32 v[50:51], v[50:51], v[242:243]
	global_store_dwordx4 v[244:245], v[48:51], off offset:528
	s_mov_b64 vcc, 0x120000
	v_lshl_add_u64 v[244:245], v[168:169], 0, vcc
	s_waitcnt vmcnt(31)
	v_lshlrev_b32_e32 v164, 16, v212
	v_and_b32_e32 v165, 0xffff0000, v212
	v_lshlrev_b32_e32 v166, 16, v213
	v_and_b32_e32 v167, 0xffff0000, v213
	v_pk_mul_f32 v[44:45], v[44:45], v[164:165]
	v_pk_mul_f32 v[46:47], v[46:47], v[166:167]
	global_store_dwordx4 v[244:245], v[44:47], off offset:0
	s_waitcnt vmcnt(31)
	v_lshlrev_b32_e32 v240, 16, v214
	v_and_b32_e32 v241, 0xffff0000, v214
	v_lshlrev_b32_e32 v242, 16, v215
	v_and_b32_e32 v243, 0xffff0000, v215
	v_pk_mul_f32 v[40:41], v[40:41], v[240:241]
	v_pk_mul_f32 v[42:43], v[42:43], v[242:243]
	global_store_dwordx4 v[244:245], v[40:43], off offset:16
	s_waitcnt vmcnt(31)
	v_lshlrev_b32_e32 v164, 16, v216
	v_and_b32_e32 v165, 0xffff0000, v216
	v_lshlrev_b32_e32 v166, 16, v217
	v_and_b32_e32 v167, 0xffff0000, v217
	v_pk_mul_f32 v[36:37], v[36:37], v[164:165]
	v_pk_mul_f32 v[38:39], v[38:39], v[166:167]
	global_store_dwordx4 v[244:245], v[36:39], off offset:512
	s_waitcnt vmcnt(31)
	v_lshlrev_b32_e32 v240, 16, v218
	v_and_b32_e32 v241, 0xffff0000, v218
	v_lshlrev_b32_e32 v242, 16, v219
	v_and_b32_e32 v243, 0xffff0000, v219
	v_pk_mul_f32 v[32:33], v[32:33], v[240:241]
	v_pk_mul_f32 v[34:35], v[34:35], v[242:243]
	global_store_dwordx4 v[244:245], v[32:35], off offset:528
	s_mov_b64 vcc, 0x140000
	v_lshl_add_u64 v[244:245], v[168:169], 0, vcc
	s_waitcnt vmcnt(31)
	v_lshlrev_b32_e32 v164, 16, v220
	v_and_b32_e32 v165, 0xffff0000, v220
	v_lshlrev_b32_e32 v166, 16, v221
	v_and_b32_e32 v167, 0xffff0000, v221
	v_pk_mul_f32 v[28:29], v[28:29], v[164:165]
	v_pk_mul_f32 v[30:31], v[30:31], v[166:167]
	global_store_dwordx4 v[244:245], v[28:31], off offset:0
	s_waitcnt vmcnt(31)
	v_lshlrev_b32_e32 v240, 16, v222
	v_and_b32_e32 v241, 0xffff0000, v222
	v_lshlrev_b32_e32 v242, 16, v223
	v_and_b32_e32 v243, 0xffff0000, v223
	v_pk_mul_f32 v[24:25], v[24:25], v[240:241]
	v_pk_mul_f32 v[26:27], v[26:27], v[242:243]
	global_store_dwordx4 v[244:245], v[24:27], off offset:16
	s_waitcnt vmcnt(31)
	v_lshlrev_b32_e32 v164, 16, v224
	v_and_b32_e32 v165, 0xffff0000, v224
	v_lshlrev_b32_e32 v166, 16, v225
	v_and_b32_e32 v167, 0xffff0000, v225
	v_pk_mul_f32 v[20:21], v[20:21], v[164:165]
	v_pk_mul_f32 v[22:23], v[22:23], v[166:167]
	global_store_dwordx4 v[244:245], v[20:23], off offset:512
	s_waitcnt vmcnt(31)
	v_lshlrev_b32_e32 v240, 16, v226
	v_and_b32_e32 v241, 0xffff0000, v226
	v_lshlrev_b32_e32 v242, 16, v227
	v_and_b32_e32 v243, 0xffff0000, v227
	v_pk_mul_f32 v[16:17], v[16:17], v[240:241]
	v_pk_mul_f32 v[18:19], v[18:19], v[242:243]
	global_store_dwordx4 v[244:245], v[16:19], off offset:528
	s_mov_b64 vcc, 0x160000
	v_lshl_add_u64 v[244:245], v[168:169], 0, vcc
	s_waitcnt vmcnt(31)
	v_lshlrev_b32_e32 v164, 16, v228
	v_and_b32_e32 v165, 0xffff0000, v228
	v_lshlrev_b32_e32 v166, 16, v229
	v_and_b32_e32 v167, 0xffff0000, v229
	v_pk_mul_f32 v[12:13], v[12:13], v[164:165]
	v_pk_mul_f32 v[14:15], v[14:15], v[166:167]
	global_store_dwordx4 v[244:245], v[12:15], off offset:0
	s_waitcnt vmcnt(31)
	v_lshlrev_b32_e32 v240, 16, v232
	v_and_b32_e32 v241, 0xffff0000, v232
	v_lshlrev_b32_e32 v242, 16, v233
	v_and_b32_e32 v243, 0xffff0000, v233
	v_pk_mul_f32 v[8:9], v[8:9], v[240:241]
	v_pk_mul_f32 v[10:11], v[10:11], v[242:243]
	global_store_dwordx4 v[244:245], v[8:11], off offset:16
	s_waitcnt vmcnt(31)
	v_lshlrev_b32_e32 v164, 16, v234
	v_and_b32_e32 v165, 0xffff0000, v234
	v_lshlrev_b32_e32 v166, 16, v235
	v_and_b32_e32 v167, 0xffff0000, v235
	v_pk_mul_f32 v[4:5], v[4:5], v[164:165]
	v_pk_mul_f32 v[6:7], v[6:7], v[166:167]
	global_store_dwordx4 v[244:245], v[4:7], off offset:512
	s_waitcnt vmcnt(31)
	v_lshlrev_b32_e32 v240, 16, v236
	v_and_b32_e32 v241, 0xffff0000, v236
	v_lshlrev_b32_e32 v242, 16, v237
	v_and_b32_e32 v243, 0xffff0000, v237
	v_pk_mul_f32 v[0:1], v[0:1], v[240:241]
	v_pk_mul_f32 v[2:3], v[2:3], v[242:243]
	global_store_dwordx4 v[244:245], v[0:3], off offset:528
	s_branch .LBB0_1232

.LBB0_1264:
	s_add_i32 s55, s34, 2
	s_add_u32 s35, vcc_lo, 0xfff80080
	s_addc_u32 s56, vcc_hi, -1
	s_add_i32 s57, 0, 0x10000
	v_add_u32_e32 v154, s57, v162
	ds_read_b128 v[142:145], v154
	ds_read_b128 v[146:149], v154 offset:1024
	ds_read_b128 v[150:153], v154 offset:2048
	ds_read_b128 v[154:157], v154 offset:3072
	s_cmp_eq_u32 s61, s34
	s_cselect_b32 s34, s39, s63
	s_cselect_b32 s95, s53, s56
	s_cselect_b32 s94, s59, s35
	s_cselect_b32 s35, s38, s54
	v_lshl_add_u64 v[158:159], vcc, 0, v[138:139]
	s_add_i32 m0, s31, 0xc000
	ds_read_b128 v[166:169], v164
	ds_read_b128 v[170:173], v164 offset:1024
	ds_read_b128 v[174:177], v164 offset:2048
	ds_read_b128 v[178:181], v164 offset:3072
	ds_read_b128 v[182:185], v164 offset:4096
	ds_read_b128 v[186:189], v164 offset:5120
	ds_read_b128 v[190:193], v164 offset:6144
	ds_read_b128 v[194:197], v164 offset:7168
	global_load_lds_dwordx4 v[158:159], off
	v_lshl_add_u64 v[158:159], vcc, 0, v[140:141]
	s_add_i32 m0, s31, 0xe000
	s_nop 0
	global_load_lds_dwordx4 v[158:159], off
	s_waitcnt lgkmcnt(8)
	s_barrier
	s_waitcnt lgkmcnt(0)
	s_setprio 1
	s_waitcnt lgkmcnt(0)
	v_mfma_f32_16x16x32_bf16 v[124:127], v[142:145], v[166:169], v[124:127]
	v_mfma_f32_16x16x32_bf16 v[120:123], v[150:153], v[166:169], v[120:123]
	v_mfma_f32_16x16x32_bf16 v[108:111], v[142:145], v[174:177], v[108:111]
	v_mfma_f32_16x16x32_bf16 v[104:107], v[150:153], v[174:177], v[104:107]
	v_mfma_f32_16x16x32_bf16 v[92:95], v[142:145], v[182:185], v[92:95]
	v_mfma_f32_16x16x32_bf16 v[88:91], v[150:153], v[182:185], v[88:91]
	v_mfma_f32_16x16x32_bf16 v[76:79], v[142:145], v[190:193], v[76:79]
	v_mfma_f32_16x16x32_bf16 v[72:75], v[150:153], v[190:193], v[72:75]
	v_mfma_f32_16x16x32_bf16 v[124:127], v[146:149], v[170:173], v[124:127]
	v_mfma_f32_16x16x32_bf16 v[120:123], v[154:157], v[170:173], v[120:123]
	v_mfma_f32_16x16x32_bf16 v[108:111], v[146:149], v[178:181], v[108:111]
	v_mfma_f32_16x16x32_bf16 v[104:107], v[154:157], v[178:181], v[104:107]
	v_mfma_f32_16x16x32_bf16 v[92:95], v[146:149], v[186:189], v[92:95]
	v_mfma_f32_16x16x32_bf16 v[88:91], v[154:157], v[186:189], v[88:91]
	v_mfma_f32_16x16x32_bf16 v[76:79], v[146:149], v[194:197], v[76:79]
	v_mfma_f32_16x16x32_bf16 v[72:75], v[154:157], v[194:197], v[72:75]
	s_setprio 0
	s_barrier
	s_add_i32 s68, 0, 0x14000
	v_add_u32_e32 v158, s68, v162
	s_add_i32 s56, s57, s41
	ds_read_b128 v[198:201], v158
	ds_read_b128 v[202:205], v158 offset:1024
	ds_read_b128 v[206:209], v158 offset:2048
	ds_read_b128 v[210:213], v158 offset:3072
	v_lshl_add_u64 v[158:159], s[34:35], 0, v[128:129]
	s_mov_b32 m0, s56
	v_lshl_add_u64 v[214:215], s[34:35], 0, v[136:137]
	global_load_lds_dwordx4 v[158:159], off
	s_add_i32 m0, s56, 0x2000
	s_nop 0
	global_load_lds_dwordx4 v[214:215], off
	s_barrier
	s_waitcnt lgkmcnt(0)
	s_setprio 1
	s_waitcnt lgkmcnt(0)
	v_mfma_f32_16x16x32_bf16 v[116:119], v[198:201], v[166:169], v[116:119]
	v_mfma_f32_16x16x32_bf16 v[112:115], v[206:209], v[166:169], v[112:115]
	v_mfma_f32_16x16x32_bf16 v[100:103], v[198:201], v[174:177], v[100:103]
	v_mfma_f32_16x16x32_bf16 v[96:99], v[206:209], v[174:177], v[96:99]
	v_mfma_f32_16x16x32_bf16 v[84:87], v[198:201], v[182:185], v[84:87]
	v_mfma_f32_16x16x32_bf16 v[80:83], v[206:209], v[182:185], v[80:83]
	v_mfma_f32_16x16x32_bf16 v[68:71], v[198:201], v[190:193], v[68:71]
	v_mfma_f32_16x16x32_bf16 v[64:67], v[206:209], v[190:193], v[64:67]
	v_mfma_f32_16x16x32_bf16 v[116:119], v[202:205], v[170:173], v[116:119]
	v_mfma_f32_16x16x32_bf16 v[112:115], v[210:213], v[170:173], v[112:115]
	v_mfma_f32_16x16x32_bf16 v[100:103], v[202:205], v[178:181], v[100:103]
	v_mfma_f32_16x16x32_bf16 v[96:99], v[210:213], v[178:181], v[96:99]
	v_mfma_f32_16x16x32_bf16 v[84:87], v[202:205], v[186:189], v[84:87]
	v_mfma_f32_16x16x32_bf16 v[80:83], v[210:213], v[186:189], v[80:83]
	v_mfma_f32_16x16x32_bf16 v[68:71], v[202:205], v[194:197], v[68:71]
	v_mfma_f32_16x16x32_bf16 v[64:67], v[210:213], v[194:197], v[64:67]
	s_setprio 0
	s_mov_b32 m0, s31
	v_lshl_add_u64 v[216:217], s[94:95], 0, v[132:133]
	s_barrier
	ds_read_b128 v[166:169], v164 offset:16384
	ds_read_b128 v[170:173], v164 offset:17408
	ds_read_b128 v[174:177], v164 offset:18432
	ds_read_b128 v[178:181], v164 offset:19456
	ds_read_b128 v[182:185], v164 offset:20480
	ds_read_b128 v[186:189], v164 offset:21504
	ds_read_b128 v[190:193], v164 offset:22528
	ds_read_b128 v[194:197], v164 offset:23552
	global_load_lds_dwordx4 v[216:217], off
	v_lshl_add_u64 v[218:219], s[94:95], 0, v[134:135]
	s_mov_b32 m0, s44
	s_nop 0
	global_load_lds_dwordx4 v[218:219], off
	s_barrier
	s_waitcnt lgkmcnt(0)
	s_setprio 1
	s_waitcnt lgkmcnt(0)
	v_mfma_f32_16x16x32_bf16 v[60:63], v[142:145], v[166:169], v[60:63]
	v_mfma_f32_16x16x32_bf16 v[56:59], v[150:153], v[166:169], v[56:59]
	v_mfma_f32_16x16x32_bf16 v[44:47], v[142:145], v[174:177], v[44:47]
	v_mfma_f32_16x16x32_bf16 v[40:43], v[150:153], v[174:177], v[40:43]
	v_mfma_f32_16x16x32_bf16 v[28:31], v[142:145], v[182:185], v[28:31]
	v_mfma_f32_16x16x32_bf16 v[24:27], v[150:153], v[182:185], v[24:27]
	v_mfma_f32_16x16x32_bf16 v[12:15], v[142:145], v[190:193], v[12:15]
	v_mfma_f32_16x16x32_bf16 v[8:11], v[150:153], v[190:193], v[8:11]
	v_mfma_f32_16x16x32_bf16 v[60:63], v[146:149], v[170:173], v[60:63]
	v_mfma_f32_16x16x32_bf16 v[56:59], v[154:157], v[170:173], v[56:59]
	v_mfma_f32_16x16x32_bf16 v[44:47], v[146:149], v[178:181], v[44:47]
	v_mfma_f32_16x16x32_bf16 v[40:43], v[154:157], v[178:181], v[40:43]
	v_mfma_f32_16x16x32_bf16 v[28:31], v[146:149], v[186:189], v[28:31]
	v_mfma_f32_16x16x32_bf16 v[24:27], v[154:157], v[186:189], v[24:27]
	v_mfma_f32_16x16x32_bf16 v[12:15], v[146:149], v[194:197], v[12:15]
	v_mfma_f32_16x16x32_bf16 v[8:11], v[154:157], v[194:197], v[8:11]
	s_setprio 0
	s_barrier
	s_add_u32 s56, s34, 0x80000
	s_addc_u32 s57, s35, 0
	s_add_i32 s68, s68, s41
	v_lshl_add_u64 v[142:143], s[56:57], 0, v[128:129]
	s_mov_b32 m0, s68
	s_nop 0
	global_load_lds_dwordx4 v[142:143], off
	v_lshl_add_u64 v[142:143], s[56:57], 0, v[136:137]
	s_add_i32 m0, s68, 0x2000
	s_nop 0
	global_load_lds_dwordx4 v[142:143], off
	s_waitcnt vmcnt(6)
	s_barrier
	s_setprio 1
	v_mfma_f32_16x16x32_bf16 v[52:55], v[198:201], v[166:169], v[52:55]
	v_mfma_f32_16x16x32_bf16 v[48:51], v[206:209], v[166:169], v[48:51]
	v_mfma_f32_16x16x32_bf16 v[36:39], v[198:201], v[174:177], v[36:39]
	v_mfma_f32_16x16x32_bf16 v[32:35], v[206:209], v[174:177], v[32:35]
	v_mfma_f32_16x16x32_bf16 v[20:23], v[198:201], v[182:185], v[20:23]
	v_mfma_f32_16x16x32_bf16 v[16:19], v[206:209], v[182:185], v[16:19]
	v_mfma_f32_16x16x32_bf16 v[4:7], v[198:201], v[190:193], v[4:7]
	v_mfma_f32_16x16x32_bf16 v[0:3], v[206:209], v[190:193], v[0:3]
	v_mfma_f32_16x16x32_bf16 v[52:55], v[202:205], v[170:173], v[52:55]
	v_mfma_f32_16x16x32_bf16 v[48:51], v[210:213], v[170:173], v[48:51]
	v_mfma_f32_16x16x32_bf16 v[36:39], v[202:205], v[178:181], v[36:39]
	v_mfma_f32_16x16x32_bf16 v[32:35], v[210:213], v[178:181], v[32:35]
	v_mfma_f32_16x16x32_bf16 v[20:23], v[202:205], v[186:189], v[20:23]
	v_mfma_f32_16x16x32_bf16 v[16:19], v[210:213], v[186:189], v[16:19]
	v_mfma_f32_16x16x32_bf16 v[4:7], v[202:205], v[194:197], v[4:7]
	v_mfma_f32_16x16x32_bf16 v[0:3], v[210:213], v[194:197], v[0:3]
	s_setprio 0
	s_add_i32 s68, 0, 0x18000
	v_add_u32_e32 v154, s68, v162
	s_barrier
	ds_read_b128 v[142:145], v154
	ds_read_b128 v[146:149], v154 offset:1024
	ds_read_b128 v[150:153], v154 offset:2048
	ds_read_b128 v[154:157], v154 offset:3072
	s_add_u32 s56, s94, 0x80000
	s_addc_u32 s57, s95, 0
	s_mov_b32 m0, s45
	v_lshl_add_u64 v[198:199], s[56:57], 0, v[132:133]
	ds_read_b128 v[166:169], v164 offset:32768
	ds_read_b128 v[170:173], v164 offset:33792
	ds_read_b128 v[174:177], v164 offset:34816
	ds_read_b128 v[178:181], v164 offset:35840
	ds_read_b128 v[182:185], v164 offset:36864
	ds_read_b128 v[186:189], v164 offset:37888
	ds_read_b128 v[190:193], v164 offset:38912
	ds_read_b128 v[194:197], v164 offset:39936
	global_load_lds_dwordx4 v[198:199], off
	v_lshl_add_u64 v[198:199], s[56:57], 0, v[134:135]
	s_mov_b32 m0, s46
	s_nop 0
	global_load_lds_dwordx4 v[198:199], off
	s_waitcnt lgkmcnt(8)
	s_barrier
	s_waitcnt lgkmcnt(0)
	s_setprio 1
	s_waitcnt lgkmcnt(0)
	v_mfma_f32_16x16x32_bf16 v[124:127], v[142:145], v[166:169], v[124:127]
	v_mfma_f32_16x16x32_bf16 v[120:123], v[150:153], v[166:169], v[120:123]
	v_mfma_f32_16x16x32_bf16 v[108:111], v[142:145], v[174:177], v[108:111]
	v_mfma_f32_16x16x32_bf16 v[104:107], v[150:153], v[174:177], v[104:107]
	v_mfma_f32_16x16x32_bf16 v[92:95], v[142:145], v[182:185], v[92:95]
	v_mfma_f32_16x16x32_bf16 v[88:91], v[150:153], v[182:185], v[88:91]
	v_mfma_f32_16x16x32_bf16 v[76:79], v[142:145], v[190:193], v[76:79]
	v_mfma_f32_16x16x32_bf16 v[72:75], v[150:153], v[190:193], v[72:75]
	v_mfma_f32_16x16x32_bf16 v[124:127], v[146:149], v[170:173], v[124:127]
	v_mfma_f32_16x16x32_bf16 v[120:123], v[154:157], v[170:173], v[120:123]
	v_mfma_f32_16x16x32_bf16 v[108:111], v[146:149], v[178:181], v[108:111]
	v_mfma_f32_16x16x32_bf16 v[104:107], v[154:157], v[178:181], v[104:107]
	v_mfma_f32_16x16x32_bf16 v[92:95], v[146:149], v[186:189], v[92:95]
	v_mfma_f32_16x16x32_bf16 v[88:91], v[154:157], v[186:189], v[88:91]
	v_mfma_f32_16x16x32_bf16 v[76:79], v[146:149], v[194:197], v[76:79]
	v_mfma_f32_16x16x32_bf16 v[72:75], v[154:157], v[194:197], v[72:75]
	s_setprio 0
	s_barrier
	s_add_i32 s56, 0, 0x1c000
	s_add_i32 s57, s68, s41
	v_add_u32_e32 v165, s56, v162
	v_lshl_add_u64 v[158:159], v[158:159], 0, s[8:9]
	s_mov_b32 m0, s57
	ds_read_b128 v[198:201], v165
	ds_read_b128 v[202:205], v165 offset:1024
	ds_read_b128 v[206:209], v165 offset:2048
	ds_read_b128 v[210:213], v165 offset:3072
	global_load_lds_dwordx4 v[158:159], off
	v_lshl_add_u64 v[158:159], v[214:215], 0, s[8:9]
	s_add_i32 m0, s57, 0x2000
	s_nop 0
	global_load_lds_dwordx4 v[158:159], off
	s_barrier
	s_waitcnt lgkmcnt(0)
	s_setprio 1
	s_waitcnt lgkmcnt(0)
	v_mfma_f32_16x16x32_bf16 v[116:119], v[198:201], v[166:169], v[116:119]
	v_mfma_f32_16x16x32_bf16 v[112:115], v[206:209], v[166:169], v[112:115]
	v_mfma_f32_16x16x32_bf16 v[100:103], v[198:201], v[174:177], v[100:103]
	v_mfma_f32_16x16x32_bf16 v[96:99], v[206:209], v[174:177], v[96:99]
	v_mfma_f32_16x16x32_bf16 v[84:87], v[198:201], v[182:185], v[84:87]
	v_mfma_f32_16x16x32_bf16 v[80:83], v[206:209], v[182:185], v[80:83]
	v_mfma_f32_16x16x32_bf16 v[68:71], v[198:201], v[190:193], v[68:71]
	v_mfma_f32_16x16x32_bf16 v[64:67], v[206:209], v[190:193], v[64:67]
	v_mfma_f32_16x16x32_bf16 v[116:119], v[202:205], v[170:173], v[116:119]
	v_mfma_f32_16x16x32_bf16 v[112:115], v[210:213], v[170:173], v[112:115]
	v_mfma_f32_16x16x32_bf16 v[100:103], v[202:205], v[178:181], v[100:103]
	v_mfma_f32_16x16x32_bf16 v[96:99], v[210:213], v[178:181], v[96:99]
	v_mfma_f32_16x16x32_bf16 v[84:87], v[202:205], v[186:189], v[84:87]
	v_mfma_f32_16x16x32_bf16 v[80:83], v[210:213], v[186:189], v[80:83]
	v_mfma_f32_16x16x32_bf16 v[68:71], v[202:205], v[194:197], v[68:71]
	v_mfma_f32_16x16x32_bf16 v[64:67], v[210:213], v[194:197], v[64:67]
	s_setprio 0
	s_mov_b32 m0, s47
	v_lshl_add_u64 v[158:159], v[216:217], 0, s[8:9]
	s_barrier
	ds_read_b128 v[166:169], v164 offset:49152
	ds_read_b128 v[170:173], v164 offset:50176
	ds_read_b128 v[174:177], v164 offset:51200
	ds_read_b128 v[178:181], v164 offset:52224
	ds_read_b128 v[182:185], v164 offset:53248
	ds_read_b128 v[186:189], v164 offset:54272
	ds_read_b128 v[190:193], v164 offset:55296
	ds_read_b128 v[194:197], v164 offset:56320
	global_load_lds_dwordx4 v[158:159], off
	v_lshl_add_u64 v[158:159], v[218:219], 0, s[8:9]
	s_mov_b32 m0, s48
	s_nop 0
	global_load_lds_dwordx4 v[158:159], off
	s_barrier
	s_waitcnt lgkmcnt(0)
	s_setprio 1
	s_waitcnt lgkmcnt(0)
	v_mfma_f32_16x16x32_bf16 v[60:63], v[142:145], v[166:169], v[60:63]
	v_mfma_f32_16x16x32_bf16 v[56:59], v[150:153], v[166:169], v[56:59]
	v_mfma_f32_16x16x32_bf16 v[44:47], v[142:145], v[174:177], v[44:47]
	v_mfma_f32_16x16x32_bf16 v[40:43], v[150:153], v[174:177], v[40:43]
	v_mfma_f32_16x16x32_bf16 v[28:31], v[142:145], v[182:185], v[28:31]
	v_mfma_f32_16x16x32_bf16 v[24:27], v[150:153], v[182:185], v[24:27]
	v_mfma_f32_16x16x32_bf16 v[12:15], v[142:145], v[190:193], v[12:15]
	v_mfma_f32_16x16x32_bf16 v[8:11], v[150:153], v[190:193], v[8:11]
	v_mfma_f32_16x16x32_bf16 v[60:63], v[146:149], v[170:173], v[60:63]
	v_mfma_f32_16x16x32_bf16 v[56:59], v[154:157], v[170:173], v[56:59]
	v_mfma_f32_16x16x32_bf16 v[44:47], v[146:149], v[178:181], v[44:47]
	v_mfma_f32_16x16x32_bf16 v[40:43], v[154:157], v[178:181], v[40:43]
	v_mfma_f32_16x16x32_bf16 v[28:31], v[146:149], v[186:189], v[28:31]
	v_mfma_f32_16x16x32_bf16 v[24:27], v[154:157], v[186:189], v[24:27]
	v_mfma_f32_16x16x32_bf16 v[12:15], v[146:149], v[194:197], v[12:15]
	v_mfma_f32_16x16x32_bf16 v[8:11], v[154:157], v[194:197], v[8:11]
	s_setprio 0
	s_barrier
	s_add_u32 s34, s34, 0x80080
	s_addc_u32 s35, s35, 0
	s_add_i32 s56, s56, s41
	v_lshl_add_u64 v[142:143], s[34:35], 0, v[128:129]
	s_mov_b32 m0, s56
	s_nop 0
	global_load_lds_dwordx4 v[142:143], off
	v_lshl_add_u64 v[142:143], s[34:35], 0, v[136:137]
	s_add_i32 m0, s56, 0x2000
	s_nop 0
	global_load_lds_dwordx4 v[142:143], off
	s_waitcnt vmcnt(6)
	s_barrier
	s_setprio 1
	v_mfma_f32_16x16x32_bf16 v[52:55], v[198:201], v[166:169], v[52:55]
	v_mfma_f32_16x16x32_bf16 v[48:51], v[206:209], v[166:169], v[48:51]
	v_mfma_f32_16x16x32_bf16 v[36:39], v[198:201], v[174:177], v[36:39]
	v_mfma_f32_16x16x32_bf16 v[32:35], v[206:209], v[174:177], v[32:35]
	v_mfma_f32_16x16x32_bf16 v[20:23], v[198:201], v[182:185], v[20:23]
	v_mfma_f32_16x16x32_bf16 v[16:19], v[206:209], v[182:185], v[16:19]
	v_mfma_f32_16x16x32_bf16 v[4:7], v[198:201], v[190:193], v[4:7]
	v_mfma_f32_16x16x32_bf16 v[0:3], v[206:209], v[190:193], v[0:3]
	v_mfma_f32_16x16x32_bf16 v[52:55], v[202:205], v[170:173], v[52:55]
	v_mfma_f32_16x16x32_bf16 v[48:51], v[210:213], v[170:173], v[48:51]
	v_mfma_f32_16x16x32_bf16 v[36:39], v[202:205], v[178:181], v[36:39]
	v_mfma_f32_16x16x32_bf16 v[32:35], v[210:213], v[178:181], v[32:35]
	v_mfma_f32_16x16x32_bf16 v[20:23], v[202:205], v[186:189], v[20:23]
	v_mfma_f32_16x16x32_bf16 v[16:19], v[210:213], v[186:189], v[16:19]
	v_mfma_f32_16x16x32_bf16 v[4:7], v[202:205], v[194:197], v[4:7]
	v_mfma_f32_16x16x32_bf16 v[0:3], v[210:213], v[194:197], v[0:3]
	s_setprio 0
	s_add_u32 vcc_lo, vcc_lo, 0x100
	s_addc_u32 vcc_hi, vcc_hi, 0
	s_add_u32 s63, s63, 0x100
	s_addc_u32 s54, s54, 0
	s_cmp_ge_i32 s55, s29
	s_mov_b32 s34, s55
	s_barrier
	s_cbranch_scc0 .LBB0_1264
	v_lshl_add_u32 v152, s30, 8, v161
	v_lshl_or_b32 v148, s28, 8, v163
	v_or_b32_e32 v150, 0x80, v148
	v_or_b32_e32 v146, 16, v152
	v_or_b32_e32 v144, 32, v152
	s_mov_b64 s[28:29], -1
	s_cmp_eq_u32 s30, 32
	v_ashrrev_i32_e32 v153, 31, v152
	v_ashrrev_i32_e32 v149, 31, v148
	v_ashrrev_i32_e32 v151, 31, v150
	v_ashrrev_i32_e32 v147, 31, v146
	v_ashrrev_i32_e32 v145, 31, v144
	v_or_b32_e32 v142, 48, v152
	s_cbranch_scc1 .LBB0_1267
	v_lshlrev_b64 v[154:155], 13, v[152:153]
	v_lshlrev_b64 v[156:157], 12, v[152:153]
	v_lshlrev_b64 v[158:159], 1, v[148:149]
	v_lshlrev_b64 v[170:171], 2, v[148:149]
	v_lshl_add_u64 v[172:173], s[0:1], 0, v[154:155]
	v_lshl_add_u64 v[172:173], v[172:173], 0, s[20:21]
	v_lshl_add_u64 v[172:173], v[172:173], 0, v[158:159]
	v_lshl_add_u64 v[174:175], s[4:5], 0, v[154:155]
	v_lshl_add_u64 v[174:175], v[174:175], 0, v[170:171]
	v_lshl_add_u64 v[176:177], s[6:7], 0, v[156:157]
	v_lshl_add_u64 v[176:177], v[176:177], 0, v[158:159]
	s_mov_b64 s[28:29], 0x0
	v_lshl_add_u64 v[178:179], v[172:173], 0, s[28:29]
	global_load_dwordx4 v[182:185], v[178:179], off
	global_load_dwordx4 v[186:189], v[178:179], off offset:256
	v_lshl_add_u64 v[178:179], v[174:175], 0, s[28:29]
	global_load_dwordx4 v[190:193], v[178:179], off offset:0
	global_load_dwordx4 v[194:197], v[178:179], off offset:16
	global_load_dwordx4 v[198:201], v[178:179], off offset:512
	global_load_dwordx4 v[202:205], v[178:179], off offset:528
	s_mov_b64 s[28:29], 0x20000
	v_lshl_add_u64 v[178:179], v[172:173], 0, s[28:29]
	global_load_dwordx4 v[206:209], v[178:179], off
	global_load_dwordx4 v[210:213], v[178:179], off offset:256
	v_lshl_add_u64 v[178:179], v[174:175], 0, s[28:29]
	global_load_dwordx4 v[214:217], v[178:179], off offset:0
	global_load_dwordx4 v[218:221], v[178:179], off offset:16
	global_load_dwordx4 v[222:225], v[178:179], off offset:512
	global_load_dwordx4 v[226:229], v[178:179], off offset:528
	s_mov_b64 s[28:29], 0x40000
	v_lshl_add_u64 v[178:179], v[172:173], 0, s[28:29]
	global_load_dwordx4 v[232:235], v[178:179], off
	global_load_dwordx4 v[236:239], v[178:179], off offset:256
	v_lshl_add_u64 v[178:179], v[174:175], 0, s[28:29]
	global_load_dwordx4 v[240:243], v[178:179], off offset:0
	global_load_dwordx4 v[244:247], v[178:179], off offset:16
	global_load_dwordx4 v[248:251], v[178:179], off offset:512
	global_load_dwordx4 v[166:169], v[178:179], off offset:528
	s_mov_b64 s[28:29], 0x0
	v_lshl_add_u64 v[180:181], v[176:177], 0, s[28:29]
	s_waitcnt vmcnt(15)
	v_lshlrev_b32_e32 v154, 16, v182
	v_and_b32_e32 v155, 0xffff0000, v182
	v_lshlrev_b32_e32 v156, 16, v183
	v_and_b32_e32 v157, 0xffff0000, v183
	v_pk_fma_f32 v[124:125], v[124:125], v[154:155], v[190:191]
	v_pk_fma_f32 v[126:127], v[126:127], v[156:157], v[192:193]
	v_cvt_pk_bf16_f32 v158, v124, v125
	v_cvt_pk_bf16_f32 v159, v126, v127
	global_store_dwordx2 v[180:181], v[158:159], off offset:0
	s_waitcnt vmcnt(15)
	v_lshlrev_b32_e32 v154, 16, v184
	v_and_b32_e32 v155, 0xffff0000, v184
	v_lshlrev_b32_e32 v156, 16, v185
	v_and_b32_e32 v157, 0xffff0000, v185
	v_pk_fma_f32 v[120:121], v[120:121], v[154:155], v[194:195]
	v_pk_fma_f32 v[122:123], v[122:123], v[156:157], v[196:197]
	v_cvt_pk_bf16_f32 v170, v120, v121
	v_cvt_pk_bf16_f32 v171, v122, v123
	global_store_dwordx2 v[180:181], v[170:171], off offset:8
	s_waitcnt vmcnt(15)
	v_lshlrev_b32_e32 v154, 16, v186
	v_and_b32_e32 v155, 0xffff0000, v186
	v_lshlrev_b32_e32 v156, 16, v187
	v_and_b32_e32 v157, 0xffff0000, v187
	v_pk_fma_f32 v[116:117], v[116:117], v[154:155], v[198:199]
	v_pk_fma_f32 v[118:119], v[118:119], v[156:157], v[200:201]
	v_cvt_pk_bf16_f32 v158, v116, v117
	v_cvt_pk_bf16_f32 v159, v118, v119
	global_store_dwordx2 v[180:181], v[158:159], off offset:256
	s_waitcnt vmcnt(15)
	v_lshlrev_b32_e32 v154, 16, v188
	v_and_b32_e32 v155, 0xffff0000, v188
	v_lshlrev_b32_e32 v156, 16, v189
	v_and_b32_e32 v157, 0xffff0000, v189
	v_pk_fma_f32 v[112:113], v[112:113], v[154:155], v[202:203]
	v_pk_fma_f32 v[114:115], v[114:115], v[156:157], v[204:205]
	v_cvt_pk_bf16_f32 v170, v112, v113
	v_cvt_pk_bf16_f32 v171, v114, v115
	global_store_dwordx2 v[180:181], v[170:171], off offset:264
	s_mov_b64 s[28:29], 0x60000
	v_lshl_add_u64 v[178:179], v[172:173], 0, s[28:29]
	global_load_dwordx4 v[182:185], v[178:179], off
	global_load_dwordx4 v[186:189], v[178:179], off offset:256
	v_lshl_add_u64 v[178:179], v[174:175], 0, s[28:29]
	global_load_dwordx4 v[190:193], v[178:179], off offset:0
	global_load_dwordx4 v[194:197], v[178:179], off offset:16
	global_load_dwordx4 v[198:201], v[178:179], off offset:512
	global_load_dwordx4 v[202:205], v[178:179], off offset:528
	s_mov_b64 s[28:29], 0x10000
	v_lshl_add_u64 v[180:181], v[176:177], 0, s[28:29]
	s_waitcnt vmcnt(19)
	v_lshlrev_b32_e32 v154, 16, v206
	v_and_b32_e32 v155, 0xffff0000, v206
	v_lshlrev_b32_e32 v156, 16, v207
	v_and_b32_e32 v157, 0xffff0000, v207
	v_pk_fma_f32 v[108:109], v[108:109], v[154:155], v[214:215]
	v_pk_fma_f32 v[110:111], v[110:111], v[156:157], v[216:217]
	v_cvt_pk_bf16_f32 v158, v108, v109
	v_cvt_pk_bf16_f32 v159, v110, v111
	global_store_dwordx2 v[180:181], v[158:159], off offset:0
	s_waitcnt vmcnt(19)
	v_lshlrev_b32_e32 v154, 16, v208
	v_and_b32_e32 v155, 0xffff0000, v208
	v_lshlrev_b32_e32 v156, 16, v209
	v_and_b32_e32 v157, 0xffff0000, v209
	v_pk_fma_f32 v[104:105], v[104:105], v[154:155], v[218:219]
	v_pk_fma_f32 v[106:107], v[106:107], v[156:157], v[220:221]
	v_cvt_pk_bf16_f32 v170, v104, v105
	v_cvt_pk_bf16_f32 v171, v106, v107
	global_store_dwordx2 v[180:181], v[170:171], off offset:8
	s_waitcnt vmcnt(19)
	v_lshlrev_b32_e32 v154, 16, v210
	v_and_b32_e32 v155, 0xffff0000, v210
	v_lshlrev_b32_e32 v156, 16, v211
	v_and_b32_e32 v157, 0xffff0000, v211
	v_pk_fma_f32 v[100:101], v[100:101], v[154:155], v[222:223]
	v_pk_fma_f32 v[102:103], v[102:103], v[156:157], v[224:225]
	v_cvt_pk_bf16_f32 v158, v100, v101
	v_cvt_pk_bf16_f32 v159, v102, v103
	global_store_dwordx2 v[180:181], v[158:159], off offset:256
	s_waitcnt vmcnt(19)
	v_lshlrev_b32_e32 v154, 16, v212
	v_and_b32_e32 v155, 0xffff0000, v212
	v_lshlrev_b32_e32 v156, 16, v213
	v_and_b32_e32 v157, 0xffff0000, v213
	v_pk_fma_f32 v[96:97], v[96:97], v[154:155], v[226:227]
	v_pk_fma_f32 v[98:99], v[98:99], v[156:157], v[228:229]
	v_cvt_pk_bf16_f32 v170, v96, v97
	v_cvt_pk_bf16_f32 v171, v98, v99
	global_store_dwordx2 v[180:181], v[170:171], off offset:264
	s_mov_b64 s[28:29], 0x100000
	v_lshl_add_u64 v[178:179], v[172:173], 0, s[28:29]
	global_load_dwordx4 v[206:209], v[178:179], off
	global_load_dwordx4 v[210:213], v[178:179], off offset:256
	v_lshl_add_u64 v[178:179], v[174:175], 0, s[28:29]
	global_load_dwordx4 v[214:217], v[178:179], off offset:0
	global_load_dwordx4 v[218:221], v[178:179], off offset:16
	global_load_dwordx4 v[222:225], v[178:179], off offset:512
	global_load_dwordx4 v[226:229], v[178:179], off offset:528
	s_mov_b64 s[28:29], 0x20000
	v_lshl_add_u64 v[180:181], v[176:177], 0, s[28:29]
	s_waitcnt vmcnt(23)
	v_lshlrev_b32_e32 v154, 16, v232
	v_and_b32_e32 v155, 0xffff0000, v232
	v_lshlrev_b32_e32 v156, 16, v233
	v_and_b32_e32 v157, 0xffff0000, v233
	v_pk_fma_f32 v[92:93], v[92:93], v[154:155], v[240:241]
	v_pk_fma_f32 v[94:95], v[94:95], v[156:157], v[242:243]
	v_cvt_pk_bf16_f32 v158, v92, v93
	v_cvt_pk_bf16_f32 v159, v94, v95
	global_store_dwordx2 v[180:181], v[158:159], off offset:0
	s_waitcnt vmcnt(23)
	v_lshlrev_b32_e32 v154, 16, v234
	v_and_b32_e32 v155, 0xffff0000, v234
	v_lshlrev_b32_e32 v156, 16, v235
	v_and_b32_e32 v157, 0xffff0000, v235
	v_pk_fma_f32 v[88:89], v[88:89], v[154:155], v[244:245]
	v_pk_fma_f32 v[90:91], v[90:91], v[156:157], v[246:247]
	v_cvt_pk_bf16_f32 v170, v88, v89
	v_cvt_pk_bf16_f32 v171, v90, v91
	global_store_dwordx2 v[180:181], v[170:171], off offset:8
	s_waitcnt vmcnt(23)
	v_lshlrev_b32_e32 v154, 16, v236
	v_and_b32_e32 v155, 0xffff0000, v236
	v_lshlrev_b32_e32 v156, 16, v237
	v_and_b32_e32 v157, 0xffff0000, v237
	v_pk_fma_f32 v[84:85], v[84:85], v[154:155], v[248:249]
	v_pk_fma_f32 v[86:87], v[86:87], v[156:157], v[250:251]
	v_cvt_pk_bf16_f32 v158, v84, v85
	v_cvt_pk_bf16_f32 v159, v86, v87
	global_store_dwordx2 v[180:181], v[158:159], off offset:256
	s_waitcnt vmcnt(23)
	v_lshlrev_b32_e32 v154, 16, v238
	v_and_b32_e32 v155, 0xffff0000, v238
	v_lshlrev_b32_e32 v156, 16, v239
	v_and_b32_e32 v157, 0xffff0000, v239
	v_pk_fma_f32 v[80:81], v[80:81], v[154:155], v[166:167]
	v_pk_fma_f32 v[82:83], v[82:83], v[156:157], v[168:169]
	v_cvt_pk_bf16_f32 v170, v80, v81
	v_cvt_pk_bf16_f32 v171, v82, v83
	global_store_dwordx2 v[180:181], v[170:171], off offset:264
	s_mov_b64 s[28:29], 0x120000
	v_lshl_add_u64 v[178:179], v[172:173], 0, s[28:29]
	global_load_dwordx4 v[232:235], v[178:179], off
	global_load_dwordx4 v[236:239], v[178:179], off offset:256
	v_lshl_add_u64 v[178:179], v[174:175], 0, s[28:29]
	global_load_dwordx4 v[240:243], v[178:179], off offset:0
	global_load_dwordx4 v[244:247], v[178:179], off offset:16
	global_load_dwordx4 v[248:251], v[178:179], off offset:512
	global_load_dwordx4 v[166:169], v[178:179], off offset:528
	s_mov_b64 s[28:29], 0x30000
	v_lshl_add_u64 v[180:181], v[176:177], 0, s[28:29]
	s_waitcnt vmcnt(23)
	v_lshlrev_b32_e32 v154, 16, v182
	v_and_b32_e32 v155, 0xffff0000, v182
	v_lshlrev_b32_e32 v156, 16, v183
	v_and_b32_e32 v157, 0xffff0000, v183
	v_pk_fma_f32 v[76:77], v[76:77], v[154:155], v[190:191]
	v_pk_fma_f32 v[78:79], v[78:79], v[156:157], v[192:193]
	v_cvt_pk_bf16_f32 v158, v76, v77
	v_cvt_pk_bf16_f32 v159, v78, v79
	global_store_dwordx2 v[180:181], v[158:159], off offset:0
	s_waitcnt vmcnt(23)
	v_lshlrev_b32_e32 v154, 16, v184
	v_and_b32_e32 v155, 0xffff0000, v184
	v_lshlrev_b32_e32 v156, 16, v185
	v_and_b32_e32 v157, 0xffff0000, v185
	v_pk_fma_f32 v[72:73], v[72:73], v[154:155], v[194:195]
	v_pk_fma_f32 v[74:75], v[74:75], v[156:157], v[196:197]
	v_cvt_pk_bf16_f32 v170, v72, v73
	v_cvt_pk_bf16_f32 v171, v74, v75
	global_store_dwordx2 v[180:181], v[170:171], off offset:8
	s_waitcnt vmcnt(23)
	v_lshlrev_b32_e32 v154, 16, v186
	v_and_b32_e32 v155, 0xffff0000, v186
	v_lshlrev_b32_e32 v156, 16, v187
	v_and_b32_e32 v157, 0xffff0000, v187
	v_pk_fma_f32 v[68:69], v[68:69], v[154:155], v[198:199]
	v_pk_fma_f32 v[70:71], v[70:71], v[156:157], v[200:201]
	v_cvt_pk_bf16_f32 v158, v68, v69
	v_cvt_pk_bf16_f32 v159, v70, v71
	global_store_dwordx2 v[180:181], v[158:159], off offset:256
	s_waitcnt vmcnt(23)
	v_lshlrev_b32_e32 v154, 16, v188
	v_and_b32_e32 v155, 0xffff0000, v188
	v_lshlrev_b32_e32 v156, 16, v189
	v_and_b32_e32 v157, 0xffff0000, v189
	v_pk_fma_f32 v[64:65], v[64:65], v[154:155], v[202:203]
	v_pk_fma_f32 v[66:67], v[66:67], v[156:157], v[204:205]
	v_cvt_pk_bf16_f32 v170, v64, v65
	v_cvt_pk_bf16_f32 v171, v66, v67
	global_store_dwordx2 v[180:181], v[170:171], off offset:264
	s_mov_b64 s[28:29], 0x140000
	v_lshl_add_u64 v[178:179], v[172:173], 0, s[28:29]
	global_load_dwordx4 v[182:185], v[178:179], off
	global_load_dwordx4 v[186:189], v[178:179], off offset:256
	v_lshl_add_u64 v[178:179], v[174:175], 0, s[28:29]
	global_load_dwordx4 v[190:193], v[178:179], off offset:0
	global_load_dwordx4 v[194:197], v[178:179], off offset:16
	global_load_dwordx4 v[198:201], v[178:179], off offset:512
	global_load_dwordx4 v[202:205], v[178:179], off offset:528
	s_mov_b64 s[28:29], 0x80000
	v_lshl_add_u64 v[180:181], v[176:177], 0, s[28:29]
	s_waitcnt vmcnt(23)
	v_lshlrev_b32_e32 v154, 16, v206
	v_and_b32_e32 v155, 0xffff0000, v206
	v_lshlrev_b32_e32 v156, 16, v207
	v_and_b32_e32 v157, 0xffff0000, v207
	v_pk_fma_f32 v[60:61], v[60:61], v[154:155], v[214:215]
	v_pk_fma_f32 v[62:63], v[62:63], v[156:157], v[216:217]
	v_cvt_pk_bf16_f32 v158, v60, v61
	v_cvt_pk_bf16_f32 v159, v62, v63
	global_store_dwordx2 v[180:181], v[158:159], off offset:0
	s_waitcnt vmcnt(23)
	v_lshlrev_b32_e32 v154, 16, v208
	v_and_b32_e32 v155, 0xffff0000, v208
	v_lshlrev_b32_e32 v156, 16, v209
	v_and_b32_e32 v157, 0xffff0000, v209
	v_pk_fma_f32 v[56:57], v[56:57], v[154:155], v[218:219]
	v_pk_fma_f32 v[58:59], v[58:59], v[156:157], v[220:221]
	v_cvt_pk_bf16_f32 v170, v56, v57
	v_cvt_pk_bf16_f32 v171, v58, v59
	global_store_dwordx2 v[180:181], v[170:171], off offset:8
	s_waitcnt vmcnt(23)
	v_lshlrev_b32_e32 v154, 16, v210
	v_and_b32_e32 v155, 0xffff0000, v210
	v_lshlrev_b32_e32 v156, 16, v211
	v_and_b32_e32 v157, 0xffff0000, v211
	v_pk_fma_f32 v[52:53], v[52:53], v[154:155], v[222:223]
	v_pk_fma_f32 v[54:55], v[54:55], v[156:157], v[224:225]
	v_cvt_pk_bf16_f32 v158, v52, v53
	v_cvt_pk_bf16_f32 v159, v54, v55
	global_store_dwordx2 v[180:181], v[158:159], off offset:256
	s_waitcnt vmcnt(23)
	v_lshlrev_b32_e32 v154, 16, v212
	v_and_b32_e32 v155, 0xffff0000, v212
	v_lshlrev_b32_e32 v156, 16, v213
	v_and_b32_e32 v157, 0xffff0000, v213
	v_pk_fma_f32 v[48:49], v[48:49], v[154:155], v[226:227]
	v_pk_fma_f32 v[50:51], v[50:51], v[156:157], v[228:229]
	v_cvt_pk_bf16_f32 v170, v48, v49
	v_cvt_pk_bf16_f32 v171, v50, v51
	global_store_dwordx2 v[180:181], v[170:171], off offset:264
	s_mov_b64 s[28:29], 0x160000
	v_lshl_add_u64 v[178:179], v[172:173], 0, s[28:29]
	global_load_dwordx4 v[206:209], v[178:179], off
	global_load_dwordx4 v[210:213], v[178:179], off offset:256
	v_lshl_add_u64 v[178:179], v[174:175], 0, s[28:29]
	global_load_dwordx4 v[214:217], v[178:179], off offset:0
	global_load_dwordx4 v[218:221], v[178:179], off offset:16
	global_load_dwordx4 v[222:225], v[178:179], off offset:512
	global_load_dwordx4 v[226:229], v[178:179], off offset:528
	s_mov_b64 s[28:29], 0x90000
	v_lshl_add_u64 v[180:181], v[176:177], 0, s[28:29]
	s_waitcnt vmcnt(23)
	v_lshlrev_b32_e32 v154, 16, v232
	v_and_b32_e32 v155, 0xffff0000, v232
	v_lshlrev_b32_e32 v156, 16, v233
	v_and_b32_e32 v157, 0xffff0000, v233
	v_pk_fma_f32 v[44:45], v[44:45], v[154:155], v[240:241]
	v_pk_fma_f32 v[46:47], v[46:47], v[156:157], v[242:243]
	v_cvt_pk_bf16_f32 v158, v44, v45
	v_cvt_pk_bf16_f32 v159, v46, v47
	global_store_dwordx2 v[180:181], v[158:159], off offset:0
	s_waitcnt vmcnt(23)
	v_lshlrev_b32_e32 v154, 16, v234
	v_and_b32_e32 v155, 0xffff0000, v234
	v_lshlrev_b32_e32 v156, 16, v235
	v_and_b32_e32 v157, 0xffff0000, v235
	v_pk_fma_f32 v[40:41], v[40:41], v[154:155], v[244:245]
	v_pk_fma_f32 v[42:43], v[42:43], v[156:157], v[246:247]
	v_cvt_pk_bf16_f32 v170, v40, v41
	v_cvt_pk_bf16_f32 v171, v42, v43
	global_store_dwordx2 v[180:181], v[170:171], off offset:8
	s_waitcnt vmcnt(23)
	v_lshlrev_b32_e32 v154, 16, v236
	v_and_b32_e32 v155, 0xffff0000, v236
	v_lshlrev_b32_e32 v156, 16, v237
	v_and_b32_e32 v157, 0xffff0000, v237
	v_pk_fma_f32 v[36:37], v[36:37], v[154:155], v[248:249]
	v_pk_fma_f32 v[38:39], v[38:39], v[156:157], v[250:251]
	v_cvt_pk_bf16_f32 v158, v36, v37
	v_cvt_pk_bf16_f32 v159, v38, v39
	global_store_dwordx2 v[180:181], v[158:159], off offset:256
	s_waitcnt vmcnt(23)
	v_lshlrev_b32_e32 v154, 16, v238
	v_and_b32_e32 v155, 0xffff0000, v238
	v_lshlrev_b32_e32 v156, 16, v239
	v_and_b32_e32 v157, 0xffff0000, v239
	v_pk_fma_f32 v[32:33], v[32:33], v[154:155], v[166:167]
	v_pk_fma_f32 v[34:35], v[34:35], v[156:157], v[168:169]
	v_cvt_pk_bf16_f32 v170, v32, v33
	v_cvt_pk_bf16_f32 v171, v34, v35
	global_store_dwordx2 v[180:181], v[170:171], off offset:264
	s_mov_b64 s[28:29], 0xa0000
	v_lshl_add_u64 v[180:181], v[176:177], 0, s[28:29]
	s_waitcnt vmcnt(17)
	v_lshlrev_b32_e32 v154, 16, v182
	v_and_b32_e32 v155, 0xffff0000, v182
	v_lshlrev_b32_e32 v156, 16, v183
	v_and_b32_e32 v157, 0xffff0000, v183
	v_pk_fma_f32 v[28:29], v[28:29], v[154:155], v[190:191]
	v_pk_fma_f32 v[30:31], v[30:31], v[156:157], v[192:193]
	v_cvt_pk_bf16_f32 v158, v28, v29
	v_cvt_pk_bf16_f32 v159, v30, v31
	global_store_dwordx2 v[180:181], v[158:159], off offset:0
	s_waitcnt vmcnt(17)
	v_lshlrev_b32_e32 v154, 16, v184
	v_and_b32_e32 v155, 0xffff0000, v184
	v_lshlrev_b32_e32 v156, 16, v185
	v_and_b32_e32 v157, 0xffff0000, v185
	v_pk_fma_f32 v[24:25], v[24:25], v[154:155], v[194:195]
	v_pk_fma_f32 v[26:27], v[26:27], v[156:157], v[196:197]
	v_cvt_pk_bf16_f32 v170, v24, v25
	v_cvt_pk_bf16_f32 v171, v26, v27
	global_store_dwordx2 v[180:181], v[170:171], off offset:8
	s_waitcnt vmcnt(17)
	v_lshlrev_b32_e32 v154, 16, v186
	v_and_b32_e32 v155, 0xffff0000, v186
	v_lshlrev_b32_e32 v156, 16, v187
	v_and_b32_e32 v157, 0xffff0000, v187
	v_pk_fma_f32 v[20:21], v[20:21], v[154:155], v[198:199]
	v_pk_fma_f32 v[22:23], v[22:23], v[156:157], v[200:201]
	v_cvt_pk_bf16_f32 v158, v20, v21
	v_cvt_pk_bf16_f32 v159, v22, v23
	global_store_dwordx2 v[180:181], v[158:159], off offset:256
	s_waitcnt vmcnt(17)
	v_lshlrev_b32_e32 v154, 16, v188
	v_and_b32_e32 v155, 0xffff0000, v188
	v_lshlrev_b32_e32 v156, 16, v189
	v_and_b32_e32 v157, 0xffff0000, v189
	v_pk_fma_f32 v[16:17], v[16:17], v[154:155], v[202:203]
	v_pk_fma_f32 v[18:19], v[18:19], v[156:157], v[204:205]
	v_cvt_pk_bf16_f32 v170, v16, v17
	v_cvt_pk_bf16_f32 v171, v18, v19
	global_store_dwordx2 v[180:181], v[170:171], off offset:264
	s_mov_b64 s[28:29], 0xb0000
	v_lshl_add_u64 v[180:181], v[176:177], 0, s[28:29]
	s_waitcnt vmcnt(11)
	v_lshlrev_b32_e32 v154, 16, v206
	v_and_b32_e32 v155, 0xffff0000, v206
	v_lshlrev_b32_e32 v156, 16, v207
	v_and_b32_e32 v157, 0xffff0000, v207
	v_pk_fma_f32 v[12:13], v[12:13], v[154:155], v[214:215]
	v_pk_fma_f32 v[14:15], v[14:15], v[156:157], v[216:217]
	v_cvt_pk_bf16_f32 v158, v12, v13
	v_cvt_pk_bf16_f32 v159, v14, v15
	global_store_dwordx2 v[180:181], v[158:159], off offset:0
	s_waitcnt vmcnt(11)
	v_lshlrev_b32_e32 v154, 16, v208
	v_and_b32_e32 v155, 0xffff0000, v208
	v_lshlrev_b32_e32 v156, 16, v209
	v_and_b32_e32 v157, 0xffff0000, v209
	v_pk_fma_f32 v[8:9], v[8:9], v[154:155], v[218:219]
	v_pk_fma_f32 v[10:11], v[10:11], v[156:157], v[220:221]
	v_cvt_pk_bf16_f32 v170, v8, v9
	v_cvt_pk_bf16_f32 v171, v10, v11
	global_store_dwordx2 v[180:181], v[170:171], off offset:8
	s_waitcnt vmcnt(11)
	v_lshlrev_b32_e32 v154, 16, v210
	v_and_b32_e32 v155, 0xffff0000, v210
	v_lshlrev_b32_e32 v156, 16, v211
	v_and_b32_e32 v157, 0xffff0000, v211
	v_pk_fma_f32 v[4:5], v[4:5], v[154:155], v[222:223]
	v_pk_fma_f32 v[6:7], v[6:7], v[156:157], v[224:225]
	v_cvt_pk_bf16_f32 v158, v4, v5
	v_cvt_pk_bf16_f32 v159, v6, v7
	global_store_dwordx2 v[180:181], v[158:159], off offset:256
	s_waitcnt vmcnt(11)
	v_lshlrev_b32_e32 v154, 16, v212
	v_and_b32_e32 v155, 0xffff0000, v212
	v_lshlrev_b32_e32 v156, 16, v213
	v_and_b32_e32 v157, 0xffff0000, v213
	v_pk_fma_f32 v[0:1], v[0:1], v[154:155], v[226:227]
	v_pk_fma_f32 v[2:3], v[2:3], v[156:157], v[228:229]
	v_cvt_pk_bf16_f32 v170, v0, v1
	v_cvt_pk_bf16_f32 v171, v2, v3
	global_store_dwordx2 v[180:181], v[170:171], off offset:264
	s_mov_b64 s[28:29], 0
.LBB0_1267:
	s_andn2_b64 vcc, exec, s[28:29]
	s_cbranch_vccnz .LBB0_1257
	s_ashr_i32 s28, s33, 10
	s_ashr_i32 s29, s28, 31
	s_lshl_b64 s[28:29], s[28:29], 21
	s_add_u32 s28, s42, s28
	s_addc_u32 s29, s43, s29
	s_sub_u32 s28, s28, 0x3c00000
	s_subb_u32 s29, s29, 0
	v_lshlrev_b64 v[154:155], 13, v[152:153]
	v_lshlrev_b64 v[156:157], 1, v[148:149]
	v_lshlrev_b64 v[158:159], 2, v[148:149]
	v_lshl_add_u64 v[170:171], s[0:1], 0, v[154:155]
	v_lshl_add_u64 v[170:171], v[170:171], 0, v[156:157]
	v_lshl_add_u64 v[170:171], v[170:171], 0, s[20:21]
	v_lshl_add_u64 v[168:169], s[28:29], 0, v[154:155]
	v_lshl_add_u64 v[168:169], v[168:169], 0, v[158:159]
	v_mov_b32_e32 v166, v170
	v_mov_b32_e32 v167, v171
	global_load_dwordx2 v[172:173], v[166:167], off offset:0
	global_load_dwordx2 v[174:175], v[166:167], off offset:8
	global_load_dwordx2 v[176:177], v[166:167], off offset:256
	global_load_dwordx2 v[178:179], v[166:167], off offset:264
	s_mov_b64 vcc, 0x20000
	v_lshl_add_u64 v[166:167], v[170:171], 0, vcc
	global_load_dwordx2 v[180:181], v[166:167], off offset:0
	global_load_dwordx2 v[182:183], v[166:167], off offset:8
	global_load_dwordx2 v[184:185], v[166:167], off offset:256
	global_load_dwordx2 v[186:187], v[166:167], off offset:264
	s_mov_b64 vcc, 0x40000
	v_lshl_add_u64 v[166:167], v[170:171], 0, vcc
	global_load_dwordx2 v[188:189], v[166:167], off offset:0
	global_load_dwordx2 v[190:191], v[166:167], off offset:8
	global_load_dwordx2 v[192:193], v[166:167], off offset:256
	global_load_dwordx2 v[194:195], v[166:167], off offset:264
	s_mov_b64 vcc, 0x60000
	v_lshl_add_u64 v[166:167], v[170:171], 0, vcc
	global_load_dwordx2 v[196:197], v[166:167], off offset:0
	global_load_dwordx2 v[198:199], v[166:167], off offset:8
	global_load_dwordx2 v[200:201], v[166:167], off offset:256
	global_load_dwordx2 v[202:203], v[166:167], off offset:264
	s_mov_b64 vcc, 0x100000
	v_lshl_add_u64 v[166:167], v[170:171], 0, vcc
	global_load_dwordx2 v[204:205], v[166:167], off offset:0
	global_load_dwordx2 v[206:207], v[166:167], off offset:8
	global_load_dwordx2 v[208:209], v[166:167], off offset:256
	global_load_dwordx2 v[210:211], v[166:167], off offset:264
	s_mov_b64 vcc, 0x120000
	v_lshl_add_u64 v[166:167], v[170:171], 0, vcc
	global_load_dwordx2 v[212:213], v[166:167], off offset:0
	global_load_dwordx2 v[214:215], v[166:167], off offset:8
	global_load_dwordx2 v[216:217], v[166:167], off offset:256
	global_load_dwordx2 v[218:219], v[166:167], off offset:264
	s_mov_b64 vcc, 0x140000
	v_lshl_add_u64 v[166:167], v[170:171], 0, vcc
	global_load_dwordx2 v[220:221], v[166:167], off offset:0
	global_load_dwordx2 v[222:223], v[166:167], off offset:8
	global_load_dwordx2 v[224:225], v[166:167], off offset:256
	global_load_dwordx2 v[226:227], v[166:167], off offset:264
	s_mov_b64 vcc, 0x160000
	v_lshl_add_u64 v[166:167], v[170:171], 0, vcc
	global_load_dwordx2 v[228:229], v[166:167], off offset:0
	global_load_dwordx2 v[232:233], v[166:167], off offset:8
	global_load_dwordx2 v[234:235], v[166:167], off offset:256
	global_load_dwordx2 v[236:237], v[166:167], off offset:264
	v_mov_b32_e32 v244, v168
	v_mov_b32_e32 v245, v169
	s_waitcnt vmcnt(31)
	v_lshlrev_b32_e32 v248, 16, v172
	v_and_b32_e32 v249, 0xffff0000, v172
	v_lshlrev_b32_e32 v250, 16, v173
	v_and_b32_e32 v251, 0xffff0000, v173
	v_pk_mul_f32 v[124:125], v[124:125], v[248:249]
	v_pk_mul_f32 v[126:127], v[126:127], v[250:251]
	global_store_dwordx4 v[244:245], v[124:127], off offset:0
	s_waitcnt vmcnt(31)
	v_lshlrev_b32_e32 v240, 16, v174
	v_and_b32_e32 v241, 0xffff0000, v174
	v_lshlrev_b32_e32 v242, 16, v175
	v_and_b32_e32 v243, 0xffff0000, v175
	v_pk_mul_f32 v[120:121], v[120:121], v[240:241]
	v_pk_mul_f32 v[122:123], v[122:123], v[242:243]
	global_store_dwordx4 v[244:245], v[120:123], off offset:16
	s_waitcnt vmcnt(31)
	v_lshlrev_b32_e32 v248, 16, v176
	v_and_b32_e32 v249, 0xffff0000, v176
	v_lshlrev_b32_e32 v250, 16, v177
	v_and_b32_e32 v251, 0xffff0000, v177
	v_pk_mul_f32 v[116:117], v[116:117], v[248:249]
	v_pk_mul_f32 v[118:119], v[118:119], v[250:251]
	global_store_dwordx4 v[244:245], v[116:119], off offset:512
	s_waitcnt vmcnt(31)
	v_lshlrev_b32_e32 v240, 16, v178
	v_and_b32_e32 v241, 0xffff0000, v178
	v_lshlrev_b32_e32 v242, 16, v179
	v_and_b32_e32 v243, 0xffff0000, v179
	v_pk_mul_f32 v[112:113], v[112:113], v[240:241]
	v_pk_mul_f32 v[114:115], v[114:115], v[242:243]
	global_store_dwordx4 v[244:245], v[112:115], off offset:528
	s_mov_b64 vcc, 0x20000
	v_lshl_add_u64 v[244:245], v[168:169], 0, vcc
	s_waitcnt vmcnt(31)
	v_lshlrev_b32_e32 v248, 16, v180
	v_and_b32_e32 v249, 0xffff0000, v180
	v_lshlrev_b32_e32 v250, 16, v181
	v_and_b32_e32 v251, 0xffff0000, v181
	v_pk_mul_f32 v[108:109], v[108:109], v[248:249]
	v_pk_mul_f32 v[110:111], v[110:111], v[250:251]
	global_store_dwordx4 v[244:245], v[108:111], off offset:0
	s_waitcnt vmcnt(31)
	v_lshlrev_b32_e32 v240, 16, v182
	v_and_b32_e32 v241, 0xffff0000, v182
	v_lshlrev_b32_e32 v242, 16, v183
	v_and_b32_e32 v243, 0xffff0000, v183
	v_pk_mul_f32 v[104:105], v[104:105], v[240:241]
	v_pk_mul_f32 v[106:107], v[106:107], v[242:243]
	global_store_dwordx4 v[244:245], v[104:107], off offset:16
	s_waitcnt vmcnt(31)
	v_lshlrev_b32_e32 v248, 16, v184
	v_and_b32_e32 v249, 0xffff0000, v184
	v_lshlrev_b32_e32 v250, 16, v185
	v_and_b32_e32 v251, 0xffff0000, v185
	v_pk_mul_f32 v[100:101], v[100:101], v[248:249]
	v_pk_mul_f32 v[102:103], v[102:103], v[250:251]
	global_store_dwordx4 v[244:245], v[100:103], off offset:512
	s_waitcnt vmcnt(31)
	v_lshlrev_b32_e32 v240, 16, v186
	v_and_b32_e32 v241, 0xffff0000, v186
	v_lshlrev_b32_e32 v242, 16, v187
	v_and_b32_e32 v243, 0xffff0000, v187
	v_pk_mul_f32 v[96:97], v[96:97], v[240:241]
	v_pk_mul_f32 v[98:99], v[98:99], v[242:243]
	global_store_dwordx4 v[244:245], v[96:99], off offset:528
	s_mov_b64 vcc, 0x40000
	v_lshl_add_u64 v[244:245], v[168:169], 0, vcc
	s_waitcnt vmcnt(31)
	v_lshlrev_b32_e32 v248, 16, v188
	v_and_b32_e32 v249, 0xffff0000, v188
	v_lshlrev_b32_e32 v250, 16, v189
	v_and_b32_e32 v251, 0xffff0000, v189
	v_pk_mul_f32 v[92:93], v[92:93], v[248:249]
	v_pk_mul_f32 v[94:95], v[94:95], v[250:251]
	global_store_dwordx4 v[244:245], v[92:95], off offset:0
	s_waitcnt vmcnt(31)
	v_lshlrev_b32_e32 v240, 16, v190
	v_and_b32_e32 v241, 0xffff0000, v190
	v_lshlrev_b32_e32 v242, 16, v191
	v_and_b32_e32 v243, 0xffff0000, v191
	v_pk_mul_f32 v[88:89], v[88:89], v[240:241]
	v_pk_mul_f32 v[90:91], v[90:91], v[242:243]
	global_store_dwordx4 v[244:245], v[88:91], off offset:16
	s_waitcnt vmcnt(31)
	v_lshlrev_b32_e32 v248, 16, v192
	v_and_b32_e32 v249, 0xffff0000, v192
	v_lshlrev_b32_e32 v250, 16, v193
	v_and_b32_e32 v251, 0xffff0000, v193
	v_pk_mul_f32 v[84:85], v[84:85], v[248:249]
	v_pk_mul_f32 v[86:87], v[86:87], v[250:251]
	global_store_dwordx4 v[244:245], v[84:87], off offset:512
	s_waitcnt vmcnt(31)
	v_lshlrev_b32_e32 v240, 16, v194
	v_and_b32_e32 v241, 0xffff0000, v194
	v_lshlrev_b32_e32 v242, 16, v195
	v_and_b32_e32 v243, 0xffff0000, v195
	v_pk_mul_f32 v[80:81], v[80:81], v[240:241]
	v_pk_mul_f32 v[82:83], v[82:83], v[242:243]
	global_store_dwordx4 v[244:245], v[80:83], off offset:528
	s_mov_b64 vcc, 0x60000
	v_lshl_add_u64 v[244:245], v[168:169], 0, vcc
	s_waitcnt vmcnt(31)
	v_lshlrev_b32_e32 v248, 16, v196
	v_and_b32_e32 v249, 0xffff0000, v196
	v_lshlrev_b32_e32 v250, 16, v197
	v_and_b32_e32 v251, 0xffff0000, v197
	v_pk_mul_f32 v[76:77], v[76:77], v[248:249]
	v_pk_mul_f32 v[78:79], v[78:79], v[250:251]
	global_store_dwordx4 v[244:245], v[76:79], off offset:0
	s_waitcnt vmcnt(31)
	v_lshlrev_b32_e32 v240, 16, v198
	v_and_b32_e32 v241, 0xffff0000, v198
	v_lshlrev_b32_e32 v242, 16, v199
	v_and_b32_e32 v243, 0xffff0000, v199
	v_pk_mul_f32 v[72:73], v[72:73], v[240:241]
	v_pk_mul_f32 v[74:75], v[74:75], v[242:243]
	global_store_dwordx4 v[244:245], v[72:75], off offset:16
	s_waitcnt vmcnt(31)
	v_lshlrev_b32_e32 v248, 16, v200
	v_and_b32_e32 v249, 0xffff0000, v200
	v_lshlrev_b32_e32 v250, 16, v201
	v_and_b32_e32 v251, 0xffff0000, v201
	v_pk_mul_f32 v[68:69], v[68:69], v[248:249]
	v_pk_mul_f32 v[70:71], v[70:71], v[250:251]
	global_store_dwordx4 v[244:245], v[68:71], off offset:512
	s_waitcnt vmcnt(31)
	v_lshlrev_b32_e32 v240, 16, v202
	v_and_b32_e32 v241, 0xffff0000, v202
	v_lshlrev_b32_e32 v242, 16, v203
	v_and_b32_e32 v243, 0xffff0000, v203
	v_pk_mul_f32 v[64:65], v[64:65], v[240:241]
	v_pk_mul_f32 v[66:67], v[66:67], v[242:243]
	global_store_dwordx4 v[244:245], v[64:67], off offset:528
	s_mov_b64 vcc, 0x100000
	v_lshl_add_u64 v[244:245], v[168:169], 0, vcc
	s_waitcnt vmcnt(31)
	v_lshlrev_b32_e32 v248, 16, v204
	v_and_b32_e32 v249, 0xffff0000, v204
	v_lshlrev_b32_e32 v250, 16, v205
	v_and_b32_e32 v251, 0xffff0000, v205
	v_pk_mul_f32 v[60:61], v[60:61], v[248:249]
	v_pk_mul_f32 v[62:63], v[62:63], v[250:251]
	global_store_dwordx4 v[244:245], v[60:63], off offset:0
	s_waitcnt vmcnt(31)
	v_lshlrev_b32_e32 v240, 16, v206
	v_and_b32_e32 v241, 0xffff0000, v206
	v_lshlrev_b32_e32 v242, 16, v207
	v_and_b32_e32 v243, 0xffff0000, v207
	v_pk_mul_f32 v[56:57], v[56:57], v[240:241]
	v_pk_mul_f32 v[58:59], v[58:59], v[242:243]
	global_store_dwordx4 v[244:245], v[56:59], off offset:16
	s_waitcnt vmcnt(31)
	v_lshlrev_b32_e32 v248, 16, v208
	v_and_b32_e32 v249, 0xffff0000, v208
	v_lshlrev_b32_e32 v250, 16, v209
	v_and_b32_e32 v251, 0xffff0000, v209
	v_pk_mul_f32 v[52:53], v[52:53], v[248:249]
	v_pk_mul_f32 v[54:55], v[54:55], v[250:251]
	global_store_dwordx4 v[244:245], v[52:55], off offset:512
	s_waitcnt vmcnt(31)
	v_lshlrev_b32_e32 v240, 16, v210
	v_and_b32_e32 v241, 0xffff0000, v210
	v_lshlrev_b32_e32 v242, 16, v211
	v_and_b32_e32 v243, 0xffff0000, v211
	v_pk_mul_f32 v[48:49], v[48:49], v[240:241]
	v_pk_mul_f32 v[50:51], v[50:51], v[242:243]
	global_store_dwordx4 v[244:245], v[48:51], off offset:528
	s_mov_b64 vcc, 0x120000
	v_lshl_add_u64 v[244:245], v[168:169], 0, vcc
	s_waitcnt vmcnt(31)
	v_lshlrev_b32_e32 v248, 16, v212
	v_and_b32_e32 v249, 0xffff0000, v212
	v_lshlrev_b32_e32 v250, 16, v213
	v_and_b32_e32 v251, 0xffff0000, v213
	v_pk_mul_f32 v[44:45], v[44:45], v[248:249]
	v_pk_mul_f32 v[46:47], v[46:47], v[250:251]
	global_store_dwordx4 v[244:245], v[44:47], off offset:0
	s_waitcnt vmcnt(31)
	v_lshlrev_b32_e32 v240, 16, v214
	v_and_b32_e32 v241, 0xffff0000, v214
	v_lshlrev_b32_e32 v242, 16, v215
	v_and_b32_e32 v243, 0xffff0000, v215
	v_pk_mul_f32 v[40:41], v[40:41], v[240:241]
	v_pk_mul_f32 v[42:43], v[42:43], v[242:243]
	global_store_dwordx4 v[244:245], v[40:43], off offset:16
	s_waitcnt vmcnt(31)
	v_lshlrev_b32_e32 v248, 16, v216
	v_and_b32_e32 v249, 0xffff0000, v216
	v_lshlrev_b32_e32 v250, 16, v217
	v_and_b32_e32 v251, 0xffff0000, v217
	v_pk_mul_f32 v[36:37], v[36:37], v[248:249]
	v_pk_mul_f32 v[38:39], v[38:39], v[250:251]
	global_store_dwordx4 v[244:245], v[36:39], off offset:512
	s_waitcnt vmcnt(31)
	v_lshlrev_b32_e32 v240, 16, v218
	v_and_b32_e32 v241, 0xffff0000, v218
	v_lshlrev_b32_e32 v242, 16, v219
	v_and_b32_e32 v243, 0xffff0000, v219
	v_pk_mul_f32 v[32:33], v[32:33], v[240:241]
	v_pk_mul_f32 v[34:35], v[34:35], v[242:243]
	global_store_dwordx4 v[244:245], v[32:35], off offset:528
	s_mov_b64 vcc, 0x140000
	v_lshl_add_u64 v[244:245], v[168:169], 0, vcc
	s_waitcnt vmcnt(31)
	v_lshlrev_b32_e32 v248, 16, v220
	v_and_b32_e32 v249, 0xffff0000, v220
	v_lshlrev_b32_e32 v250, 16, v221
	v_and_b32_e32 v251, 0xffff0000, v221
	v_pk_mul_f32 v[28:29], v[28:29], v[248:249]
	v_pk_mul_f32 v[30:31], v[30:31], v[250:251]
	global_store_dwordx4 v[244:245], v[28:31], off offset:0
	s_waitcnt vmcnt(31)
	v_lshlrev_b32_e32 v240, 16, v222
	v_and_b32_e32 v241, 0xffff0000, v222
	v_lshlrev_b32_e32 v242, 16, v223
	v_and_b32_e32 v243, 0xffff0000, v223
	v_pk_mul_f32 v[24:25], v[24:25], v[240:241]
	v_pk_mul_f32 v[26:27], v[26:27], v[242:243]
	global_store_dwordx4 v[244:245], v[24:27], off offset:16
	s_waitcnt vmcnt(31)
	v_lshlrev_b32_e32 v248, 16, v224
	v_and_b32_e32 v249, 0xffff0000, v224
	v_lshlrev_b32_e32 v250, 16, v225
	v_and_b32_e32 v251, 0xffff0000, v225
	v_pk_mul_f32 v[20:21], v[20:21], v[248:249]
	v_pk_mul_f32 v[22:23], v[22:23], v[250:251]
	global_store_dwordx4 v[244:245], v[20:23], off offset:512
	s_waitcnt vmcnt(31)
	v_lshlrev_b32_e32 v240, 16, v226
	v_and_b32_e32 v241, 0xffff0000, v226
	v_lshlrev_b32_e32 v242, 16, v227
	v_and_b32_e32 v243, 0xffff0000, v227
	v_pk_mul_f32 v[16:17], v[16:17], v[240:241]
	v_pk_mul_f32 v[18:19], v[18:19], v[242:243]
	global_store_dwordx4 v[244:245], v[16:19], off offset:528
	s_mov_b64 vcc, 0x160000
	v_lshl_add_u64 v[244:245], v[168:169], 0, vcc
	s_waitcnt vmcnt(31)
	v_lshlrev_b32_e32 v248, 16, v228
	v_and_b32_e32 v249, 0xffff0000, v228
	v_lshlrev_b32_e32 v250, 16, v229
	v_and_b32_e32 v251, 0xffff0000, v229
	v_pk_mul_f32 v[12:13], v[12:13], v[248:249]
	v_pk_mul_f32 v[14:15], v[14:15], v[250:251]
	global_store_dwordx4 v[244:245], v[12:15], off offset:0
	s_waitcnt vmcnt(31)
	v_lshlrev_b32_e32 v240, 16, v232
	v_and_b32_e32 v241, 0xffff0000, v232
	v_lshlrev_b32_e32 v242, 16, v233
	v_and_b32_e32 v243, 0xffff0000, v233
	v_pk_mul_f32 v[8:9], v[8:9], v[240:241]
	v_pk_mul_f32 v[10:11], v[10:11], v[242:243]
	global_store_dwordx4 v[244:245], v[8:11], off offset:16
	s_waitcnt vmcnt(31)
	v_lshlrev_b32_e32 v248, 16, v234
	v_and_b32_e32 v249, 0xffff0000, v234
	v_lshlrev_b32_e32 v250, 16, v235
	v_and_b32_e32 v251, 0xffff0000, v235
	v_pk_mul_f32 v[4:5], v[4:5], v[248:249]
	v_pk_mul_f32 v[6:7], v[6:7], v[250:251]
	global_store_dwordx4 v[244:245], v[4:7], off offset:512
	s_waitcnt vmcnt(31)
	v_lshlrev_b32_e32 v240, 16, v236
	v_and_b32_e32 v241, 0xffff0000, v236
	v_lshlrev_b32_e32 v242, 16, v237
	v_and_b32_e32 v243, 0xffff0000, v237
	v_pk_mul_f32 v[0:1], v[0:1], v[240:241]
	v_pk_mul_f32 v[2:3], v[2:3], v[242:243]
	global_store_dwordx4 v[244:245], v[0:3], off offset:528
	s_branch .LBB0_1257

.LBB0_1412:
	s_andn2_b64 vcc, exec, s[24:25]
	s_cbranch_vccnz .LBB0_1400
	v_or_b32_e32 v152, 16, v142
	v_or_b32_e32 v150, 32, v142
	v_or_b32_e32 v148, 48, v142
	v_lshlrev_b64 v[154:155], 11, v[142:143]
	s_andn2_b64 vcc, exec, s[6:7]
	v_lshlrev_b64 v[144:145], 2, v[146:147]
	v_ashrrev_i32_e32 v153, 31, v152
	v_ashrrev_i32_e32 v151, 31, v150
	v_ashrrev_i32_e32 v149, 31, v148
	s_cbranch_vccnz .LBB0_1417
	v_readlane_b32 s64, v253, 21
	v_readlane_b32 s65, v253, 22
	v_readlane_b32 s66, v253, 23
	v_readlane_b32 s67, v253, 24
	v_readlane_b32 s68, v253, 25
	v_readlane_b32 s69, v253, 26
	v_readlane_b32 s70, v253, 27
	v_readlane_b32 s71, v253, 28
	v_readlane_b32 s72, v253, 29
	v_readlane_b32 s73, v253, 30
	v_readlane_b32 s74, v253, 31
	v_readlane_b32 s75, v253, 32
	v_readlane_b32 s76, v253, 33
	v_readlane_b32 s77, v253, 34
	v_readlane_b32 s78, v253, 35
	v_readlane_b32 s79, v253, 36
	v_lshlrev_b64 v[156:157], 13, v[142:143]
	v_lshl_add_u64 v[168:169], s[64:65], 0, v[156:157]
	v_lshl_add_u64 v[168:169], v[168:169], 0, v[144:145]
	v_lshl_add_u64 v[170:171], s[92:93], 0, v[156:157]
	v_lshl_add_u64 v[170:171], v[170:171], 0, v[144:145]
	v_mov_b32_e32 v164, v168
	v_mov_b32_e32 v165, v169
	global_load_dwordx4 v[172:175], v[164:165], off offset:0
	global_load_dwordx4 v[176:179], v[164:165], off offset:16
	global_load_dwordx4 v[180:183], v[164:165], off offset:512
	global_load_dwordx4 v[184:187], v[164:165], off offset:528
	s_mov_b64 s[20:21], 0x20000
	v_lshl_add_u64 v[164:165], v[168:169], 0, s[20:21]
	global_load_dwordx4 v[188:191], v[164:165], off offset:0
	global_load_dwordx4 v[192:195], v[164:165], off offset:16
	global_load_dwordx4 v[196:199], v[164:165], off offset:512
	global_load_dwordx4 v[200:203], v[164:165], off offset:528
	s_mov_b64 s[20:21], 0x40000
	v_lshl_add_u64 v[164:165], v[168:169], 0, s[20:21]
	global_load_dwordx4 v[204:207], v[164:165], off offset:0
	global_load_dwordx4 v[208:211], v[164:165], off offset:16
	global_load_dwordx4 v[212:215], v[164:165], off offset:512
	global_load_dwordx4 v[216:219], v[164:165], off offset:528
	s_mov_b64 s[20:21], 0x60000
	v_lshl_add_u64 v[164:165], v[168:169], 0, s[20:21]
	global_load_dwordx4 v[220:223], v[164:165], off offset:0
	global_load_dwordx4 v[224:227], v[164:165], off offset:16
	global_load_dwordx4 v[232:235], v[164:165], off offset:512
	global_load_dwordx4 v[236:239], v[164:165], off offset:528
	v_mov_b32_e32 v166, v170
	v_mov_b32_e32 v167, v171
	s_waitcnt vmcnt(15)
	v_pk_fma_f32 v[126:127], v[174:175], s[10:11], v[126:127] op_sel_hi:[1,0,1]
	v_pk_fma_f32 v[124:125], v[172:173], s[10:11], v[124:125] op_sel_hi:[1,0,1]
	global_store_dwordx4 v[166:167], v[124:127], off offset:0
	s_waitcnt vmcnt(15)
	v_pk_fma_f32 v[122:123], v[178:179], s[10:11], v[122:123] op_sel_hi:[1,0,1]
	v_pk_fma_f32 v[120:121], v[176:177], s[10:11], v[120:121] op_sel_hi:[1,0,1]
	global_store_dwordx4 v[166:167], v[120:123], off offset:16
	s_waitcnt vmcnt(15)
	v_pk_fma_f32 v[118:119], v[182:183], s[10:11], v[118:119] op_sel_hi:[1,0,1]
	v_pk_fma_f32 v[116:117], v[180:181], s[10:11], v[116:117] op_sel_hi:[1,0,1]
	global_store_dwordx4 v[166:167], v[116:119], off offset:512
	s_waitcnt vmcnt(15)
	v_pk_fma_f32 v[114:115], v[186:187], s[10:11], v[114:115] op_sel_hi:[1,0,1]
	v_pk_fma_f32 v[112:113], v[184:185], s[10:11], v[112:113] op_sel_hi:[1,0,1]
	global_store_dwordx4 v[166:167], v[112:115], off offset:528
	s_mov_b64 s[20:21], 0x100000
	v_lshl_add_u64 v[164:165], v[168:169], 0, s[20:21]
	global_load_dwordx4 v[172:175], v[164:165], off offset:0
	global_load_dwordx4 v[176:179], v[164:165], off offset:16
	global_load_dwordx4 v[180:183], v[164:165], off offset:512
	global_load_dwordx4 v[184:187], v[164:165], off offset:528
	s_mov_b64 s[20:21], 0x20000
	v_lshl_add_u64 v[166:167], v[170:171], 0, s[20:21]
	s_waitcnt vmcnt(19)
	v_pk_fma_f32 v[110:111], v[190:191], s[10:11], v[110:111] op_sel_hi:[1,0,1]
	v_pk_fma_f32 v[108:109], v[188:189], s[10:11], v[108:109] op_sel_hi:[1,0,1]
	global_store_dwordx4 v[166:167], v[108:111], off offset:0
	s_waitcnt vmcnt(19)
	v_pk_fma_f32 v[106:107], v[194:195], s[10:11], v[106:107] op_sel_hi:[1,0,1]
	v_pk_fma_f32 v[104:105], v[192:193], s[10:11], v[104:105] op_sel_hi:[1,0,1]
	global_store_dwordx4 v[166:167], v[104:107], off offset:16
	s_waitcnt vmcnt(19)
	v_pk_fma_f32 v[102:103], v[198:199], s[10:11], v[102:103] op_sel_hi:[1,0,1]
	v_pk_fma_f32 v[100:101], v[196:197], s[10:11], v[100:101] op_sel_hi:[1,0,1]
	global_store_dwordx4 v[166:167], v[100:103], off offset:512
	s_waitcnt vmcnt(19)
	v_pk_fma_f32 v[98:99], v[202:203], s[10:11], v[98:99] op_sel_hi:[1,0,1]
	v_pk_fma_f32 v[96:97], v[200:201], s[10:11], v[96:97] op_sel_hi:[1,0,1]
	global_store_dwordx4 v[166:167], v[96:99], off offset:528
	s_mov_b64 s[20:21], 0x120000
	v_lshl_add_u64 v[164:165], v[168:169], 0, s[20:21]
	global_load_dwordx4 v[188:191], v[164:165], off offset:0
	global_load_dwordx4 v[192:195], v[164:165], off offset:16
	global_load_dwordx4 v[196:199], v[164:165], off offset:512
	global_load_dwordx4 v[200:203], v[164:165], off offset:528
	s_mov_b64 s[20:21], 0x40000
	v_lshl_add_u64 v[166:167], v[170:171], 0, s[20:21]
	s_waitcnt vmcnt(23)
	v_pk_fma_f32 v[94:95], v[206:207], s[10:11], v[94:95] op_sel_hi:[1,0,1]
	v_pk_fma_f32 v[92:93], v[204:205], s[10:11], v[92:93] op_sel_hi:[1,0,1]
	global_store_dwordx4 v[166:167], v[92:95], off offset:0
	s_waitcnt vmcnt(23)
	v_pk_fma_f32 v[90:91], v[210:211], s[10:11], v[90:91] op_sel_hi:[1,0,1]
	v_pk_fma_f32 v[88:89], v[208:209], s[10:11], v[88:89] op_sel_hi:[1,0,1]
	global_store_dwordx4 v[166:167], v[88:91], off offset:16
	s_waitcnt vmcnt(23)
	v_pk_fma_f32 v[86:87], v[214:215], s[10:11], v[86:87] op_sel_hi:[1,0,1]
	v_pk_fma_f32 v[84:85], v[212:213], s[10:11], v[84:85] op_sel_hi:[1,0,1]
	global_store_dwordx4 v[166:167], v[84:87], off offset:512
	s_waitcnt vmcnt(23)
	v_pk_fma_f32 v[82:83], v[218:219], s[10:11], v[82:83] op_sel_hi:[1,0,1]
	v_pk_fma_f32 v[80:81], v[216:217], s[10:11], v[80:81] op_sel_hi:[1,0,1]
	global_store_dwordx4 v[166:167], v[80:83], off offset:528
	s_mov_b64 s[20:21], 0x140000
	v_lshl_add_u64 v[164:165], v[168:169], 0, s[20:21]
	global_load_dwordx4 v[204:207], v[164:165], off offset:0
	global_load_dwordx4 v[208:211], v[164:165], off offset:16
	global_load_dwordx4 v[212:215], v[164:165], off offset:512
	global_load_dwordx4 v[216:219], v[164:165], off offset:528
	s_mov_b64 s[20:21], 0x60000
	v_lshl_add_u64 v[166:167], v[170:171], 0, s[20:21]
	s_waitcnt vmcnt(27)
	v_pk_fma_f32 v[78:79], v[222:223], s[10:11], v[78:79] op_sel_hi:[1,0,1]
	v_pk_fma_f32 v[76:77], v[220:221], s[10:11], v[76:77] op_sel_hi:[1,0,1]
	global_store_dwordx4 v[166:167], v[76:79], off offset:0
	s_waitcnt vmcnt(27)
	v_pk_fma_f32 v[74:75], v[226:227], s[10:11], v[74:75] op_sel_hi:[1,0,1]
	v_pk_fma_f32 v[72:73], v[224:225], s[10:11], v[72:73] op_sel_hi:[1,0,1]
	global_store_dwordx4 v[166:167], v[72:75], off offset:16
	s_waitcnt vmcnt(27)
	v_pk_fma_f32 v[70:71], v[234:235], s[10:11], v[70:71] op_sel_hi:[1,0,1]
	v_pk_fma_f32 v[68:69], v[232:233], s[10:11], v[68:69] op_sel_hi:[1,0,1]
	global_store_dwordx4 v[166:167], v[68:71], off offset:512
	s_waitcnt vmcnt(27)
	v_pk_fma_f32 v[66:67], v[238:239], s[10:11], v[66:67] op_sel_hi:[1,0,1]
	v_pk_fma_f32 v[64:65], v[236:237], s[10:11], v[64:65] op_sel_hi:[1,0,1]
	global_store_dwordx4 v[166:167], v[64:67], off offset:528
	s_mov_b64 s[20:21], 0x160000
	v_lshl_add_u64 v[164:165], v[168:169], 0, s[20:21]
	global_load_dwordx4 v[220:223], v[164:165], off offset:0
	global_load_dwordx4 v[224:227], v[164:165], off offset:16
	global_load_dwordx4 v[232:235], v[164:165], off offset:512
	global_load_dwordx4 v[236:239], v[164:165], off offset:528
	s_mov_b64 s[20:21], 0x100000
	v_lshl_add_u64 v[166:167], v[170:171], 0, s[20:21]
	s_waitcnt vmcnt(27)
	v_pk_fma_f32 v[62:63], v[174:175], s[10:11], v[62:63] op_sel_hi:[1,0,1]
	v_pk_fma_f32 v[60:61], v[172:173], s[10:11], v[60:61] op_sel_hi:[1,0,1]
	global_store_dwordx4 v[166:167], v[60:63], off offset:0
	s_waitcnt vmcnt(27)
	v_pk_fma_f32 v[58:59], v[178:179], s[10:11], v[58:59] op_sel_hi:[1,0,1]
	v_pk_fma_f32 v[56:57], v[176:177], s[10:11], v[56:57] op_sel_hi:[1,0,1]
	global_store_dwordx4 v[166:167], v[56:59], off offset:16
	s_waitcnt vmcnt(27)
	v_pk_fma_f32 v[54:55], v[182:183], s[10:11], v[54:55] op_sel_hi:[1,0,1]
	v_pk_fma_f32 v[52:53], v[180:181], s[10:11], v[52:53] op_sel_hi:[1,0,1]
	global_store_dwordx4 v[166:167], v[52:55], off offset:512
	s_waitcnt vmcnt(27)
	v_pk_fma_f32 v[50:51], v[186:187], s[10:11], v[50:51] op_sel_hi:[1,0,1]
	v_pk_fma_f32 v[48:49], v[184:185], s[10:11], v[48:49] op_sel_hi:[1,0,1]
	global_store_dwordx4 v[166:167], v[48:51], off offset:528
	s_mov_b64 s[20:21], 0x120000
	v_lshl_add_u64 v[166:167], v[170:171], 0, s[20:21]
	s_waitcnt vmcnt(23)
	v_pk_fma_f32 v[46:47], v[190:191], s[10:11], v[46:47] op_sel_hi:[1,0,1]
	v_pk_fma_f32 v[44:45], v[188:189], s[10:11], v[44:45] op_sel_hi:[1,0,1]
	global_store_dwordx4 v[166:167], v[44:47], off offset:0
	s_waitcnt vmcnt(23)
	v_pk_fma_f32 v[42:43], v[194:195], s[10:11], v[42:43] op_sel_hi:[1,0,1]
	v_pk_fma_f32 v[40:41], v[192:193], s[10:11], v[40:41] op_sel_hi:[1,0,1]
	global_store_dwordx4 v[166:167], v[40:43], off offset:16
	s_waitcnt vmcnt(23)
	v_pk_fma_f32 v[38:39], v[198:199], s[10:11], v[38:39] op_sel_hi:[1,0,1]
	v_pk_fma_f32 v[36:37], v[196:197], s[10:11], v[36:37] op_sel_hi:[1,0,1]
	global_store_dwordx4 v[166:167], v[36:39], off offset:512
	s_waitcnt vmcnt(23)
	v_pk_fma_f32 v[34:35], v[202:203], s[10:11], v[34:35] op_sel_hi:[1,0,1]
	v_pk_fma_f32 v[32:33], v[200:201], s[10:11], v[32:33] op_sel_hi:[1,0,1]
	global_store_dwordx4 v[166:167], v[32:35], off offset:528
	s_mov_b64 s[20:21], 0x140000
	v_lshl_add_u64 v[166:167], v[170:171], 0, s[20:21]
	s_waitcnt vmcnt(19)
	v_pk_fma_f32 v[30:31], v[206:207], s[10:11], v[30:31] op_sel_hi:[1,0,1]
	v_pk_fma_f32 v[28:29], v[204:205], s[10:11], v[28:29] op_sel_hi:[1,0,1]
	global_store_dwordx4 v[166:167], v[28:31], off offset:0
	s_waitcnt vmcnt(19)
	v_pk_fma_f32 v[26:27], v[210:211], s[10:11], v[26:27] op_sel_hi:[1,0,1]
	v_pk_fma_f32 v[24:25], v[208:209], s[10:11], v[24:25] op_sel_hi:[1,0,1]
	global_store_dwordx4 v[166:167], v[24:27], off offset:16
	s_waitcnt vmcnt(19)
	v_pk_fma_f32 v[22:23], v[214:215], s[10:11], v[22:23] op_sel_hi:[1,0,1]
	v_pk_fma_f32 v[20:21], v[212:213], s[10:11], v[20:21] op_sel_hi:[1,0,1]
	global_store_dwordx4 v[166:167], v[20:23], off offset:512
	s_waitcnt vmcnt(19)
	v_pk_fma_f32 v[18:19], v[218:219], s[10:11], v[18:19] op_sel_hi:[1,0,1]
	v_pk_fma_f32 v[16:17], v[216:217], s[10:11], v[16:17] op_sel_hi:[1,0,1]
	global_store_dwordx4 v[166:167], v[16:19], off offset:528
	s_mov_b64 s[20:21], 0x160000
	v_lshl_add_u64 v[166:167], v[170:171], 0, s[20:21]
	s_waitcnt vmcnt(15)
	v_pk_fma_f32 v[14:15], v[222:223], s[10:11], v[14:15] op_sel_hi:[1,0,1]
	v_pk_fma_f32 v[12:13], v[220:221], s[10:11], v[12:13] op_sel_hi:[1,0,1]
	global_store_dwordx4 v[166:167], v[12:15], off offset:0
	s_waitcnt vmcnt(15)
	v_pk_fma_f32 v[10:11], v[226:227], s[10:11], v[10:11] op_sel_hi:[1,0,1]
	v_pk_fma_f32 v[8:9], v[224:225], s[10:11], v[8:9] op_sel_hi:[1,0,1]
	global_store_dwordx4 v[166:167], v[8:11], off offset:16
	s_waitcnt vmcnt(15)
	v_pk_fma_f32 v[6:7], v[234:235], s[10:11], v[6:7] op_sel_hi:[1,0,1]
	v_pk_fma_f32 v[4:5], v[232:233], s[10:11], v[4:5] op_sel_hi:[1,0,1]
	global_store_dwordx4 v[166:167], v[4:7], off offset:512
	s_waitcnt vmcnt(15)
	v_pk_fma_f32 v[2:3], v[238:239], s[10:11], v[2:3] op_sel_hi:[1,0,1]
	v_pk_fma_f32 v[0:1], v[236:237], s[10:11], v[0:1] op_sel_hi:[1,0,1]
	global_store_dwordx4 v[166:167], v[0:3], off offset:528
	s_mov_b64 s[20:21], 0x160000
	s_cbranch_execnz .LBB0_1400
	s_branch .LBB0_1399

.LBB0_1950:
	s_andn2_b64 vcc, exec, s[2:3]
	s_cbranch_vccnz .LBB0_1940
	v_lshlrev_b64 v[154:155], 12, v[142:143]
	v_lshlrev_b64 v[156:157], 13, v[142:143]
	v_lshlrev_b64 v[158:159], 1, v[146:147]
	v_lshlrev_b64 v[160:161], 2, v[146:147]
	v_lshl_add_u64 v[170:171], s[82:83], 0, v[154:155]
	v_lshl_add_u64 v[170:171], v[170:171], 0, v[158:159]
	v_lshl_add_u64 v[168:169], s[80:81], 0, v[156:157]
	v_lshl_add_u64 v[168:169], v[168:169], 0, v[160:161]
	v_mov_b32_e32 v166, v170
	v_mov_b32_e32 v167, v171
	global_load_dwordx2 v[172:173], v[166:167], off offset:0
	global_load_dwordx2 v[174:175], v[166:167], off offset:8
	global_load_dwordx2 v[176:177], v[166:167], off offset:256
	global_load_dwordx2 v[178:179], v[166:167], off offset:264
	s_mov_b64 s[100:101], 0x10000
	v_lshl_add_u64 v[166:167], v[170:171], 0, s[100:101]
	global_load_dwordx2 v[180:181], v[166:167], off offset:0
	global_load_dwordx2 v[182:183], v[166:167], off offset:8
	global_load_dwordx2 v[184:185], v[166:167], off offset:256
	global_load_dwordx2 v[186:187], v[166:167], off offset:264
	s_mov_b64 s[100:101], 0x20000
	v_lshl_add_u64 v[166:167], v[170:171], 0, s[100:101]
	global_load_dwordx2 v[188:189], v[166:167], off offset:0
	global_load_dwordx2 v[190:191], v[166:167], off offset:8
	global_load_dwordx2 v[192:193], v[166:167], off offset:256
	global_load_dwordx2 v[194:195], v[166:167], off offset:264
	s_mov_b64 s[100:101], 0x30000
	v_lshl_add_u64 v[166:167], v[170:171], 0, s[100:101]
	global_load_dwordx2 v[196:197], v[166:167], off offset:0
	global_load_dwordx2 v[198:199], v[166:167], off offset:8
	global_load_dwordx2 v[200:201], v[166:167], off offset:256
	global_load_dwordx2 v[202:203], v[166:167], off offset:264
	s_mov_b64 s[100:101], 0x80000
	v_lshl_add_u64 v[166:167], v[170:171], 0, s[100:101]
	global_load_dwordx2 v[204:205], v[166:167], off offset:0
	global_load_dwordx2 v[206:207], v[166:167], off offset:8
	global_load_dwordx2 v[208:209], v[166:167], off offset:256
	global_load_dwordx2 v[210:211], v[166:167], off offset:264
	s_mov_b64 s[100:101], 0x90000
	v_lshl_add_u64 v[166:167], v[170:171], 0, s[100:101]
	global_load_dwordx2 v[212:213], v[166:167], off offset:0
	global_load_dwordx2 v[214:215], v[166:167], off offset:8
	global_load_dwordx2 v[216:217], v[166:167], off offset:256
	global_load_dwordx2 v[218:219], v[166:167], off offset:264
	s_mov_b64 s[100:101], 0xa0000
	v_lshl_add_u64 v[166:167], v[170:171], 0, s[100:101]
	global_load_dwordx2 v[220:221], v[166:167], off offset:0
	global_load_dwordx2 v[222:223], v[166:167], off offset:8
	global_load_dwordx2 v[224:225], v[166:167], off offset:256
	global_load_dwordx2 v[226:227], v[166:167], off offset:264
	s_mov_b64 s[100:101], 0xb0000
	v_lshl_add_u64 v[166:167], v[170:171], 0, s[100:101]
	global_load_dwordx2 v[228:229], v[166:167], off offset:0
	global_load_dwordx2 v[232:233], v[166:167], off offset:8
	global_load_dwordx2 v[234:235], v[166:167], off offset:256
	global_load_dwordx2 v[236:237], v[166:167], off offset:264
	v_mov_b32_e32 v244, v168
	v_mov_b32_e32 v245, v169
	s_waitcnt vmcnt(31)
	v_lshlrev_b32_e32 v162, 16, v172
	v_and_b32_e32 v163, 0xffff0000, v172
	v_lshlrev_b32_e32 v164, 16, v173
	v_and_b32_e32 v165, 0xffff0000, v173
	v_pk_fma_f32 v[124:125], v[162:163], s[86:87], v[124:125] op_sel_hi:[1,0,1]
	v_pk_fma_f32 v[126:127], v[164:165], s[86:87], v[126:127] op_sel_hi:[1,0,1]
	global_store_dwordx4 v[244:245], v[124:127], off offset:0
	s_waitcnt vmcnt(31)
	v_lshlrev_b32_e32 v240, 16, v174
	v_and_b32_e32 v241, 0xffff0000, v174
	v_lshlrev_b32_e32 v242, 16, v175
	v_and_b32_e32 v243, 0xffff0000, v175
	v_pk_fma_f32 v[120:121], v[240:241], s[86:87], v[120:121] op_sel_hi:[1,0,1]
	v_pk_fma_f32 v[122:123], v[242:243], s[86:87], v[122:123] op_sel_hi:[1,0,1]
	global_store_dwordx4 v[244:245], v[120:123], off offset:16
	s_waitcnt vmcnt(31)
	v_lshlrev_b32_e32 v162, 16, v176
	v_and_b32_e32 v163, 0xffff0000, v176
	v_lshlrev_b32_e32 v164, 16, v177
	v_and_b32_e32 v165, 0xffff0000, v177
	v_pk_fma_f32 v[116:117], v[162:163], s[86:87], v[116:117] op_sel_hi:[1,0,1]
	v_pk_fma_f32 v[118:119], v[164:165], s[86:87], v[118:119] op_sel_hi:[1,0,1]
	global_store_dwordx4 v[244:245], v[116:119], off offset:512
	s_waitcnt vmcnt(31)
	v_lshlrev_b32_e32 v240, 16, v178
	v_and_b32_e32 v241, 0xffff0000, v178
	v_lshlrev_b32_e32 v242, 16, v179
	v_and_b32_e32 v243, 0xffff0000, v179
	v_pk_fma_f32 v[112:113], v[240:241], s[86:87], v[112:113] op_sel_hi:[1,0,1]
	v_pk_fma_f32 v[114:115], v[242:243], s[86:87], v[114:115] op_sel_hi:[1,0,1]
	global_store_dwordx4 v[244:245], v[112:115], off offset:528
	s_mov_b64 s[100:101], 0x20000
	v_lshl_add_u64 v[244:245], v[168:169], 0, s[100:101]
	s_waitcnt vmcnt(31)
	v_lshlrev_b32_e32 v162, 16, v180
	v_and_b32_e32 v163, 0xffff0000, v180
	v_lshlrev_b32_e32 v164, 16, v181
	v_and_b32_e32 v165, 0xffff0000, v181
	v_pk_fma_f32 v[108:109], v[162:163], s[86:87], v[108:109] op_sel_hi:[1,0,1]
	v_pk_fma_f32 v[110:111], v[164:165], s[86:87], v[110:111] op_sel_hi:[1,0,1]
	global_store_dwordx4 v[244:245], v[108:111], off offset:0
	s_waitcnt vmcnt(31)
	v_lshlrev_b32_e32 v240, 16, v182
	v_and_b32_e32 v241, 0xffff0000, v182
	v_lshlrev_b32_e32 v242, 16, v183
	v_and_b32_e32 v243, 0xffff0000, v183
	v_pk_fma_f32 v[104:105], v[240:241], s[86:87], v[104:105] op_sel_hi:[1,0,1]
	v_pk_fma_f32 v[106:107], v[242:243], s[86:87], v[106:107] op_sel_hi:[1,0,1]
	global_store_dwordx4 v[244:245], v[104:107], off offset:16
	s_waitcnt vmcnt(31)
	v_lshlrev_b32_e32 v162, 16, v184
	v_and_b32_e32 v163, 0xffff0000, v184
	v_lshlrev_b32_e32 v164, 16, v185
	v_and_b32_e32 v165, 0xffff0000, v185
	v_pk_fma_f32 v[100:101], v[162:163], s[86:87], v[100:101] op_sel_hi:[1,0,1]
	v_pk_fma_f32 v[102:103], v[164:165], s[86:87], v[102:103] op_sel_hi:[1,0,1]
	global_store_dwordx4 v[244:245], v[100:103], off offset:512
	s_waitcnt vmcnt(31)
	v_lshlrev_b32_e32 v240, 16, v186
	v_and_b32_e32 v241, 0xffff0000, v186
	v_lshlrev_b32_e32 v242, 16, v187
	v_and_b32_e32 v243, 0xffff0000, v187
	v_pk_fma_f32 v[96:97], v[240:241], s[86:87], v[96:97] op_sel_hi:[1,0,1]
	v_pk_fma_f32 v[98:99], v[242:243], s[86:87], v[98:99] op_sel_hi:[1,0,1]
	global_store_dwordx4 v[244:245], v[96:99], off offset:528
	s_mov_b64 s[100:101], 0x40000
	v_lshl_add_u64 v[244:245], v[168:169], 0, s[100:101]
	s_waitcnt vmcnt(31)
	v_lshlrev_b32_e32 v162, 16, v188
	v_and_b32_e32 v163, 0xffff0000, v188
	v_lshlrev_b32_e32 v164, 16, v189
	v_and_b32_e32 v165, 0xffff0000, v189
	v_pk_fma_f32 v[92:93], v[162:163], s[86:87], v[92:93] op_sel_hi:[1,0,1]
	v_pk_fma_f32 v[94:95], v[164:165], s[86:87], v[94:95] op_sel_hi:[1,0,1]
	global_store_dwordx4 v[244:245], v[92:95], off offset:0
	s_waitcnt vmcnt(31)
	v_lshlrev_b32_e32 v240, 16, v190
	v_and_b32_e32 v241, 0xffff0000, v190
	v_lshlrev_b32_e32 v242, 16, v191
	v_and_b32_e32 v243, 0xffff0000, v191
	v_pk_fma_f32 v[88:89], v[240:241], s[86:87], v[88:89] op_sel_hi:[1,0,1]
	v_pk_fma_f32 v[90:91], v[242:243], s[86:87], v[90:91] op_sel_hi:[1,0,1]
	global_store_dwordx4 v[244:245], v[88:91], off offset:16
	s_waitcnt vmcnt(31)
	v_lshlrev_b32_e32 v162, 16, v192
	v_and_b32_e32 v163, 0xffff0000, v192
	v_lshlrev_b32_e32 v164, 16, v193
	v_and_b32_e32 v165, 0xffff0000, v193
	v_pk_fma_f32 v[84:85], v[162:163], s[86:87], v[84:85] op_sel_hi:[1,0,1]
	v_pk_fma_f32 v[86:87], v[164:165], s[86:87], v[86:87] op_sel_hi:[1,0,1]
	global_store_dwordx4 v[244:245], v[84:87], off offset:512
	s_waitcnt vmcnt(31)
	v_lshlrev_b32_e32 v240, 16, v194
	v_and_b32_e32 v241, 0xffff0000, v194
	v_lshlrev_b32_e32 v242, 16, v195
	v_and_b32_e32 v243, 0xffff0000, v195
	v_pk_fma_f32 v[80:81], v[240:241], s[86:87], v[80:81] op_sel_hi:[1,0,1]
	v_pk_fma_f32 v[82:83], v[242:243], s[86:87], v[82:83] op_sel_hi:[1,0,1]
	global_store_dwordx4 v[244:245], v[80:83], off offset:528
	s_mov_b64 s[100:101], 0x60000
	v_lshl_add_u64 v[244:245], v[168:169], 0, s[100:101]
	s_waitcnt vmcnt(31)
	v_lshlrev_b32_e32 v162, 16, v196
	v_and_b32_e32 v163, 0xffff0000, v196
	v_lshlrev_b32_e32 v164, 16, v197
	v_and_b32_e32 v165, 0xffff0000, v197
	v_pk_fma_f32 v[76:77], v[162:163], s[86:87], v[76:77] op_sel_hi:[1,0,1]
	v_pk_fma_f32 v[78:79], v[164:165], s[86:87], v[78:79] op_sel_hi:[1,0,1]
	global_store_dwordx4 v[244:245], v[76:79], off offset:0
	s_waitcnt vmcnt(31)
	v_lshlrev_b32_e32 v240, 16, v198
	v_and_b32_e32 v241, 0xffff0000, v198
	v_lshlrev_b32_e32 v242, 16, v199
	v_and_b32_e32 v243, 0xffff0000, v199
	v_pk_fma_f32 v[72:73], v[240:241], s[86:87], v[72:73] op_sel_hi:[1,0,1]
	v_pk_fma_f32 v[74:75], v[242:243], s[86:87], v[74:75] op_sel_hi:[1,0,1]
	global_store_dwordx4 v[244:245], v[72:75], off offset:16
	s_waitcnt vmcnt(31)
	v_lshlrev_b32_e32 v162, 16, v200
	v_and_b32_e32 v163, 0xffff0000, v200
	v_lshlrev_b32_e32 v164, 16, v201
	v_and_b32_e32 v165, 0xffff0000, v201
	v_pk_fma_f32 v[68:69], v[162:163], s[86:87], v[68:69] op_sel_hi:[1,0,1]
	v_pk_fma_f32 v[70:71], v[164:165], s[86:87], v[70:71] op_sel_hi:[1,0,1]
	global_store_dwordx4 v[244:245], v[68:71], off offset:512
	s_waitcnt vmcnt(31)
	v_lshlrev_b32_e32 v240, 16, v202
	v_and_b32_e32 v241, 0xffff0000, v202
	v_lshlrev_b32_e32 v242, 16, v203
	v_and_b32_e32 v243, 0xffff0000, v203
	v_pk_fma_f32 v[64:65], v[240:241], s[86:87], v[64:65] op_sel_hi:[1,0,1]
	v_pk_fma_f32 v[66:67], v[242:243], s[86:87], v[66:67] op_sel_hi:[1,0,1]
	global_store_dwordx4 v[244:245], v[64:67], off offset:528
	s_mov_b64 s[100:101], 0x100000
	v_lshl_add_u64 v[244:245], v[168:169], 0, s[100:101]
	s_waitcnt vmcnt(31)
	v_lshlrev_b32_e32 v162, 16, v204
	v_and_b32_e32 v163, 0xffff0000, v204
	v_lshlrev_b32_e32 v164, 16, v205
	v_and_b32_e32 v165, 0xffff0000, v205
	v_pk_fma_f32 v[60:61], v[162:163], s[86:87], v[60:61] op_sel_hi:[1,0,1]
	v_pk_fma_f32 v[62:63], v[164:165], s[86:87], v[62:63] op_sel_hi:[1,0,1]
	global_store_dwordx4 v[244:245], v[60:63], off offset:0
	s_waitcnt vmcnt(31)
	v_lshlrev_b32_e32 v240, 16, v206
	v_and_b32_e32 v241, 0xffff0000, v206
	v_lshlrev_b32_e32 v242, 16, v207
	v_and_b32_e32 v243, 0xffff0000, v207
	v_pk_fma_f32 v[56:57], v[240:241], s[86:87], v[56:57] op_sel_hi:[1,0,1]
	v_pk_fma_f32 v[58:59], v[242:243], s[86:87], v[58:59] op_sel_hi:[1,0,1]
	global_store_dwordx4 v[244:245], v[56:59], off offset:16
	s_waitcnt vmcnt(31)
	v_lshlrev_b32_e32 v162, 16, v208
	v_and_b32_e32 v163, 0xffff0000, v208
	v_lshlrev_b32_e32 v164, 16, v209
	v_and_b32_e32 v165, 0xffff0000, v209
	v_pk_fma_f32 v[52:53], v[162:163], s[86:87], v[52:53] op_sel_hi:[1,0,1]
	v_pk_fma_f32 v[54:55], v[164:165], s[86:87], v[54:55] op_sel_hi:[1,0,1]
	global_store_dwordx4 v[244:245], v[52:55], off offset:512
	s_waitcnt vmcnt(31)
	v_lshlrev_b32_e32 v240, 16, v210
	v_and_b32_e32 v241, 0xffff0000, v210
	v_lshlrev_b32_e32 v242, 16, v211
	v_and_b32_e32 v243, 0xffff0000, v211
	v_pk_fma_f32 v[48:49], v[240:241], s[86:87], v[48:49] op_sel_hi:[1,0,1]
	v_pk_fma_f32 v[50:51], v[242:243], s[86:87], v[50:51] op_sel_hi:[1,0,1]
	global_store_dwordx4 v[244:245], v[48:51], off offset:528
	s_mov_b64 s[100:101], 0x120000
	v_lshl_add_u64 v[244:245], v[168:169], 0, s[100:101]
	s_waitcnt vmcnt(31)
	v_lshlrev_b32_e32 v162, 16, v212
	v_and_b32_e32 v163, 0xffff0000, v212
	v_lshlrev_b32_e32 v164, 16, v213
	v_and_b32_e32 v165, 0xffff0000, v213
	v_pk_fma_f32 v[44:45], v[162:163], s[86:87], v[44:45] op_sel_hi:[1,0,1]
	v_pk_fma_f32 v[46:47], v[164:165], s[86:87], v[46:47] op_sel_hi:[1,0,1]
	global_store_dwordx4 v[244:245], v[44:47], off offset:0
	s_waitcnt vmcnt(31)
	v_lshlrev_b32_e32 v240, 16, v214
	v_and_b32_e32 v241, 0xffff0000, v214
	v_lshlrev_b32_e32 v242, 16, v215
	v_and_b32_e32 v243, 0xffff0000, v215
	v_pk_fma_f32 v[40:41], v[240:241], s[86:87], v[40:41] op_sel_hi:[1,0,1]
	v_pk_fma_f32 v[42:43], v[242:243], s[86:87], v[42:43] op_sel_hi:[1,0,1]
	global_store_dwordx4 v[244:245], v[40:43], off offset:16
	s_waitcnt vmcnt(31)
	v_lshlrev_b32_e32 v162, 16, v216
	v_and_b32_e32 v163, 0xffff0000, v216
	v_lshlrev_b32_e32 v164, 16, v217
	v_and_b32_e32 v165, 0xffff0000, v217
	v_pk_fma_f32 v[36:37], v[162:163], s[86:87], v[36:37] op_sel_hi:[1,0,1]
	v_pk_fma_f32 v[38:39], v[164:165], s[86:87], v[38:39] op_sel_hi:[1,0,1]
	global_store_dwordx4 v[244:245], v[36:39], off offset:512
	s_waitcnt vmcnt(31)
	v_lshlrev_b32_e32 v240, 16, v218
	v_and_b32_e32 v241, 0xffff0000, v218
	v_lshlrev_b32_e32 v242, 16, v219
	v_and_b32_e32 v243, 0xffff0000, v219
	v_pk_fma_f32 v[32:33], v[240:241], s[86:87], v[32:33] op_sel_hi:[1,0,1]
	v_pk_fma_f32 v[34:35], v[242:243], s[86:87], v[34:35] op_sel_hi:[1,0,1]
	global_store_dwordx4 v[244:245], v[32:35], off offset:528
	s_mov_b64 s[100:101], 0x140000
	v_lshl_add_u64 v[244:245], v[168:169], 0, s[100:101]
	s_waitcnt vmcnt(31)
	v_lshlrev_b32_e32 v162, 16, v220
	v_and_b32_e32 v163, 0xffff0000, v220
	v_lshlrev_b32_e32 v164, 16, v221
	v_and_b32_e32 v165, 0xffff0000, v221
	v_pk_fma_f32 v[28:29], v[162:163], s[86:87], v[28:29] op_sel_hi:[1,0,1]
	v_pk_fma_f32 v[30:31], v[164:165], s[86:87], v[30:31] op_sel_hi:[1,0,1]
	global_store_dwordx4 v[244:245], v[28:31], off offset:0
	s_waitcnt vmcnt(31)
	v_lshlrev_b32_e32 v240, 16, v222
	v_and_b32_e32 v241, 0xffff0000, v222
	v_lshlrev_b32_e32 v242, 16, v223
	v_and_b32_e32 v243, 0xffff0000, v223
	v_pk_fma_f32 v[24:25], v[240:241], s[86:87], v[24:25] op_sel_hi:[1,0,1]
	v_pk_fma_f32 v[26:27], v[242:243], s[86:87], v[26:27] op_sel_hi:[1,0,1]
	global_store_dwordx4 v[244:245], v[24:27], off offset:16
	s_waitcnt vmcnt(31)
	v_lshlrev_b32_e32 v162, 16, v224
	v_and_b32_e32 v163, 0xffff0000, v224
	v_lshlrev_b32_e32 v164, 16, v225
	v_and_b32_e32 v165, 0xffff0000, v225
	v_pk_fma_f32 v[20:21], v[162:163], s[86:87], v[20:21] op_sel_hi:[1,0,1]
	v_pk_fma_f32 v[22:23], v[164:165], s[86:87], v[22:23] op_sel_hi:[1,0,1]
	global_store_dwordx4 v[244:245], v[20:23], off offset:512
	s_waitcnt vmcnt(31)
	v_lshlrev_b32_e32 v240, 16, v226
	v_and_b32_e32 v241, 0xffff0000, v226
	v_lshlrev_b32_e32 v242, 16, v227
	v_and_b32_e32 v243, 0xffff0000, v227
	v_pk_fma_f32 v[16:17], v[240:241], s[86:87], v[16:17] op_sel_hi:[1,0,1]
	v_pk_fma_f32 v[18:19], v[242:243], s[86:87], v[18:19] op_sel_hi:[1,0,1]
	global_store_dwordx4 v[244:245], v[16:19], off offset:528
	s_mov_b64 s[100:101], 0x160000
	v_lshl_add_u64 v[244:245], v[168:169], 0, s[100:101]
	s_waitcnt vmcnt(31)
	v_lshlrev_b32_e32 v162, 16, v228
	v_and_b32_e32 v163, 0xffff0000, v228
	v_lshlrev_b32_e32 v164, 16, v229
	v_and_b32_e32 v165, 0xffff0000, v229
	v_pk_fma_f32 v[12:13], v[162:163], s[86:87], v[12:13] op_sel_hi:[1,0,1]
	v_pk_fma_f32 v[14:15], v[164:165], s[86:87], v[14:15] op_sel_hi:[1,0,1]
	global_store_dwordx4 v[244:245], v[12:15], off offset:0
	s_waitcnt vmcnt(31)
	v_lshlrev_b32_e32 v240, 16, v232
	v_and_b32_e32 v241, 0xffff0000, v232
	v_lshlrev_b32_e32 v242, 16, v233
	v_and_b32_e32 v243, 0xffff0000, v233
	v_pk_fma_f32 v[8:9], v[240:241], s[86:87], v[8:9] op_sel_hi:[1,0,1]
	v_pk_fma_f32 v[10:11], v[242:243], s[86:87], v[10:11] op_sel_hi:[1,0,1]
	global_store_dwordx4 v[244:245], v[8:11], off offset:16
	s_waitcnt vmcnt(31)
	v_lshlrev_b32_e32 v162, 16, v234
	v_and_b32_e32 v163, 0xffff0000, v234
	v_lshlrev_b32_e32 v164, 16, v235
	v_and_b32_e32 v165, 0xffff0000, v235
	v_pk_fma_f32 v[4:5], v[162:163], s[86:87], v[4:5] op_sel_hi:[1,0,1]
	v_pk_fma_f32 v[6:7], v[164:165], s[86:87], v[6:7] op_sel_hi:[1,0,1]
	global_store_dwordx4 v[244:245], v[4:7], off offset:512
	s_waitcnt vmcnt(31)
	v_lshlrev_b32_e32 v240, 16, v236
	v_and_b32_e32 v241, 0xffff0000, v236
	v_lshlrev_b32_e32 v242, 16, v237
	v_and_b32_e32 v243, 0xffff0000, v237
	v_pk_fma_f32 v[0:1], v[240:241], s[86:87], v[0:1] op_sel_hi:[1,0,1]
	v_pk_fma_f32 v[2:3], v[242:243], s[86:87], v[2:3] op_sel_hi:[1,0,1]
	global_store_dwordx4 v[244:245], v[0:3], off offset:528
	s_branch .LBB0_1940

.LBB0_2368:
	s_andn2_b64 vcc, exec, s[6:7]
	s_cbranch_vccnz .LBB0_2356
	v_lshlrev_b64 v[154:155], 12, v[142:143]
	v_lshlrev_b64 v[156:157], 13, v[142:143]
	v_lshlrev_b64 v[158:159], 1, v[146:147]
	v_lshlrev_b64 v[160:161], 2, v[146:147]
	v_lshl_add_u64 v[170:171], s[82:83], 0, v[154:155]
	v_lshl_add_u64 v[170:171], v[170:171], 0, v[158:159]
	v_lshl_add_u64 v[168:169], s[80:81], 0, v[156:157]
	v_lshl_add_u64 v[168:169], v[168:169], 0, v[160:161]
	v_mov_b32_e32 v166, v170
	v_mov_b32_e32 v167, v171
	global_load_dwordx2 v[172:173], v[166:167], off offset:0
	global_load_dwordx2 v[174:175], v[166:167], off offset:8
	global_load_dwordx2 v[176:177], v[166:167], off offset:256
	global_load_dwordx2 v[178:179], v[166:167], off offset:264
	s_mov_b64 s[100:101], 0x10000
	v_lshl_add_u64 v[166:167], v[170:171], 0, s[100:101]
	global_load_dwordx2 v[180:181], v[166:167], off offset:0
	global_load_dwordx2 v[182:183], v[166:167], off offset:8
	global_load_dwordx2 v[184:185], v[166:167], off offset:256
	global_load_dwordx2 v[186:187], v[166:167], off offset:264
	s_mov_b64 s[100:101], 0x20000
	v_lshl_add_u64 v[166:167], v[170:171], 0, s[100:101]
	global_load_dwordx2 v[188:189], v[166:167], off offset:0
	global_load_dwordx2 v[190:191], v[166:167], off offset:8
	global_load_dwordx2 v[192:193], v[166:167], off offset:256
	global_load_dwordx2 v[194:195], v[166:167], off offset:264
	s_mov_b64 s[100:101], 0x30000
	v_lshl_add_u64 v[166:167], v[170:171], 0, s[100:101]
	global_load_dwordx2 v[196:197], v[166:167], off offset:0
	global_load_dwordx2 v[198:199], v[166:167], off offset:8
	global_load_dwordx2 v[200:201], v[166:167], off offset:256
	global_load_dwordx2 v[202:203], v[166:167], off offset:264
	s_mov_b64 s[100:101], 0x80000
	v_lshl_add_u64 v[166:167], v[170:171], 0, s[100:101]
	global_load_dwordx2 v[204:205], v[166:167], off offset:0
	global_load_dwordx2 v[206:207], v[166:167], off offset:8
	global_load_dwordx2 v[208:209], v[166:167], off offset:256
	global_load_dwordx2 v[210:211], v[166:167], off offset:264
	s_mov_b64 s[100:101], 0x90000
	v_lshl_add_u64 v[166:167], v[170:171], 0, s[100:101]
	global_load_dwordx2 v[212:213], v[166:167], off offset:0
	global_load_dwordx2 v[214:215], v[166:167], off offset:8
	global_load_dwordx2 v[216:217], v[166:167], off offset:256
	global_load_dwordx2 v[218:219], v[166:167], off offset:264
	s_mov_b64 s[100:101], 0xa0000
	v_lshl_add_u64 v[166:167], v[170:171], 0, s[100:101]
	global_load_dwordx2 v[220:221], v[166:167], off offset:0
	global_load_dwordx2 v[222:223], v[166:167], off offset:8
	global_load_dwordx2 v[224:225], v[166:167], off offset:256
	global_load_dwordx2 v[226:227], v[166:167], off offset:264
	s_mov_b64 s[100:101], 0xb0000
	v_lshl_add_u64 v[166:167], v[170:171], 0, s[100:101]
	global_load_dwordx2 v[228:229], v[166:167], off offset:0
	global_load_dwordx2 v[232:233], v[166:167], off offset:8
	global_load_dwordx2 v[234:235], v[166:167], off offset:256
	global_load_dwordx2 v[236:237], v[166:167], off offset:264
	v_mov_b32_e32 v244, v168
	v_mov_b32_e32 v245, v169
	s_waitcnt vmcnt(31)
	v_lshlrev_b32_e32 v162, 16, v172
	v_and_b32_e32 v163, 0xffff0000, v172
	v_lshlrev_b32_e32 v164, 16, v173
	v_and_b32_e32 v165, 0xffff0000, v173
	v_pk_fma_f32 v[124:125], v[162:163], s[88:89], v[124:125] op_sel_hi:[1,0,1]
	v_pk_fma_f32 v[126:127], v[164:165], s[88:89], v[126:127] op_sel_hi:[1,0,1]
	global_store_dwordx4 v[244:245], v[124:127], off offset:0
	s_waitcnt vmcnt(31)
	v_lshlrev_b32_e32 v240, 16, v174
	v_and_b32_e32 v241, 0xffff0000, v174
	v_lshlrev_b32_e32 v242, 16, v175
	v_and_b32_e32 v243, 0xffff0000, v175
	v_pk_fma_f32 v[120:121], v[240:241], s[88:89], v[120:121] op_sel_hi:[1,0,1]
	v_pk_fma_f32 v[122:123], v[242:243], s[88:89], v[122:123] op_sel_hi:[1,0,1]
	global_store_dwordx4 v[244:245], v[120:123], off offset:16
	s_waitcnt vmcnt(31)
	v_lshlrev_b32_e32 v162, 16, v176
	v_and_b32_e32 v163, 0xffff0000, v176
	v_lshlrev_b32_e32 v164, 16, v177
	v_and_b32_e32 v165, 0xffff0000, v177
	v_pk_fma_f32 v[116:117], v[162:163], s[88:89], v[116:117] op_sel_hi:[1,0,1]
	v_pk_fma_f32 v[118:119], v[164:165], s[88:89], v[118:119] op_sel_hi:[1,0,1]
	global_store_dwordx4 v[244:245], v[116:119], off offset:512
	s_waitcnt vmcnt(31)
	v_lshlrev_b32_e32 v240, 16, v178
	v_and_b32_e32 v241, 0xffff0000, v178
	v_lshlrev_b32_e32 v242, 16, v179
	v_and_b32_e32 v243, 0xffff0000, v179
	v_pk_fma_f32 v[112:113], v[240:241], s[88:89], v[112:113] op_sel_hi:[1,0,1]
	v_pk_fma_f32 v[114:115], v[242:243], s[88:89], v[114:115] op_sel_hi:[1,0,1]
	global_store_dwordx4 v[244:245], v[112:115], off offset:528
	s_mov_b64 s[100:101], 0x20000
	v_lshl_add_u64 v[244:245], v[168:169], 0, s[100:101]
	s_waitcnt vmcnt(31)
	v_lshlrev_b32_e32 v162, 16, v180
	v_and_b32_e32 v163, 0xffff0000, v180
	v_lshlrev_b32_e32 v164, 16, v181
	v_and_b32_e32 v165, 0xffff0000, v181
	v_pk_fma_f32 v[108:109], v[162:163], s[88:89], v[108:109] op_sel_hi:[1,0,1]
	v_pk_fma_f32 v[110:111], v[164:165], s[88:89], v[110:111] op_sel_hi:[1,0,1]
	global_store_dwordx4 v[244:245], v[108:111], off offset:0
	s_waitcnt vmcnt(31)
	v_lshlrev_b32_e32 v240, 16, v182
	v_and_b32_e32 v241, 0xffff0000, v182
	v_lshlrev_b32_e32 v242, 16, v183
	v_and_b32_e32 v243, 0xffff0000, v183
	v_pk_fma_f32 v[104:105], v[240:241], s[88:89], v[104:105] op_sel_hi:[1,0,1]
	v_pk_fma_f32 v[106:107], v[242:243], s[88:89], v[106:107] op_sel_hi:[1,0,1]
	global_store_dwordx4 v[244:245], v[104:107], off offset:16
	s_waitcnt vmcnt(31)
	v_lshlrev_b32_e32 v162, 16, v184
	v_and_b32_e32 v163, 0xffff0000, v184
	v_lshlrev_b32_e32 v164, 16, v185
	v_and_b32_e32 v165, 0xffff0000, v185
	v_pk_fma_f32 v[100:101], v[162:163], s[88:89], v[100:101] op_sel_hi:[1,0,1]
	v_pk_fma_f32 v[102:103], v[164:165], s[88:89], v[102:103] op_sel_hi:[1,0,1]
	global_store_dwordx4 v[244:245], v[100:103], off offset:512
	s_waitcnt vmcnt(31)
	v_lshlrev_b32_e32 v240, 16, v186
	v_and_b32_e32 v241, 0xffff0000, v186
	v_lshlrev_b32_e32 v242, 16, v187
	v_and_b32_e32 v243, 0xffff0000, v187
	v_pk_fma_f32 v[96:97], v[240:241], s[88:89], v[96:97] op_sel_hi:[1,0,1]
	v_pk_fma_f32 v[98:99], v[242:243], s[88:89], v[98:99] op_sel_hi:[1,0,1]
	global_store_dwordx4 v[244:245], v[96:99], off offset:528
	s_mov_b64 s[100:101], 0x40000
	v_lshl_add_u64 v[244:245], v[168:169], 0, s[100:101]
	s_waitcnt vmcnt(31)
	v_lshlrev_b32_e32 v162, 16, v188
	v_and_b32_e32 v163, 0xffff0000, v188
	v_lshlrev_b32_e32 v164, 16, v189
	v_and_b32_e32 v165, 0xffff0000, v189
	v_pk_fma_f32 v[92:93], v[162:163], s[88:89], v[92:93] op_sel_hi:[1,0,1]
	v_pk_fma_f32 v[94:95], v[164:165], s[88:89], v[94:95] op_sel_hi:[1,0,1]
	global_store_dwordx4 v[244:245], v[92:95], off offset:0
	s_waitcnt vmcnt(31)
	v_lshlrev_b32_e32 v240, 16, v190
	v_and_b32_e32 v241, 0xffff0000, v190
	v_lshlrev_b32_e32 v242, 16, v191
	v_and_b32_e32 v243, 0xffff0000, v191
	v_pk_fma_f32 v[88:89], v[240:241], s[88:89], v[88:89] op_sel_hi:[1,0,1]
	v_pk_fma_f32 v[90:91], v[242:243], s[88:89], v[90:91] op_sel_hi:[1,0,1]
	global_store_dwordx4 v[244:245], v[88:91], off offset:16
	s_waitcnt vmcnt(31)
	v_lshlrev_b32_e32 v162, 16, v192
	v_and_b32_e32 v163, 0xffff0000, v192
	v_lshlrev_b32_e32 v164, 16, v193
	v_and_b32_e32 v165, 0xffff0000, v193
	v_pk_fma_f32 v[84:85], v[162:163], s[88:89], v[84:85] op_sel_hi:[1,0,1]
	v_pk_fma_f32 v[86:87], v[164:165], s[88:89], v[86:87] op_sel_hi:[1,0,1]
	global_store_dwordx4 v[244:245], v[84:87], off offset:512
	s_waitcnt vmcnt(31)
	v_lshlrev_b32_e32 v240, 16, v194
	v_and_b32_e32 v241, 0xffff0000, v194
	v_lshlrev_b32_e32 v242, 16, v195
	v_and_b32_e32 v243, 0xffff0000, v195
	v_pk_fma_f32 v[80:81], v[240:241], s[88:89], v[80:81] op_sel_hi:[1,0,1]
	v_pk_fma_f32 v[82:83], v[242:243], s[88:89], v[82:83] op_sel_hi:[1,0,1]
	global_store_dwordx4 v[244:245], v[80:83], off offset:528
	s_mov_b64 s[100:101], 0x60000
	v_lshl_add_u64 v[244:245], v[168:169], 0, s[100:101]
	s_waitcnt vmcnt(31)
	v_lshlrev_b32_e32 v162, 16, v196
	v_and_b32_e32 v163, 0xffff0000, v196
	v_lshlrev_b32_e32 v164, 16, v197
	v_and_b32_e32 v165, 0xffff0000, v197
	v_pk_fma_f32 v[76:77], v[162:163], s[88:89], v[76:77] op_sel_hi:[1,0,1]
	v_pk_fma_f32 v[78:79], v[164:165], s[88:89], v[78:79] op_sel_hi:[1,0,1]
	global_store_dwordx4 v[244:245], v[76:79], off offset:0
	s_waitcnt vmcnt(31)
	v_lshlrev_b32_e32 v240, 16, v198
	v_and_b32_e32 v241, 0xffff0000, v198
	v_lshlrev_b32_e32 v242, 16, v199
	v_and_b32_e32 v243, 0xffff0000, v199
	v_pk_fma_f32 v[72:73], v[240:241], s[88:89], v[72:73] op_sel_hi:[1,0,1]
	v_pk_fma_f32 v[74:75], v[242:243], s[88:89], v[74:75] op_sel_hi:[1,0,1]
	global_store_dwordx4 v[244:245], v[72:75], off offset:16
	s_waitcnt vmcnt(31)
	v_lshlrev_b32_e32 v162, 16, v200
	v_and_b32_e32 v163, 0xffff0000, v200
	v_lshlrev_b32_e32 v164, 16, v201
	v_and_b32_e32 v165, 0xffff0000, v201
	v_pk_fma_f32 v[68:69], v[162:163], s[88:89], v[68:69] op_sel_hi:[1,0,1]
	v_pk_fma_f32 v[70:71], v[164:165], s[88:89], v[70:71] op_sel_hi:[1,0,1]
	global_store_dwordx4 v[244:245], v[68:71], off offset:512
	s_waitcnt vmcnt(31)
	v_lshlrev_b32_e32 v240, 16, v202
	v_and_b32_e32 v241, 0xffff0000, v202
	v_lshlrev_b32_e32 v242, 16, v203
	v_and_b32_e32 v243, 0xffff0000, v203
	v_pk_fma_f32 v[64:65], v[240:241], s[88:89], v[64:65] op_sel_hi:[1,0,1]
	v_pk_fma_f32 v[66:67], v[242:243], s[88:89], v[66:67] op_sel_hi:[1,0,1]
	global_store_dwordx4 v[244:245], v[64:67], off offset:528
	s_mov_b64 s[100:101], 0x100000
	v_lshl_add_u64 v[244:245], v[168:169], 0, s[100:101]
	s_waitcnt vmcnt(31)
	v_lshlrev_b32_e32 v162, 16, v204
	v_and_b32_e32 v163, 0xffff0000, v204
	v_lshlrev_b32_e32 v164, 16, v205
	v_and_b32_e32 v165, 0xffff0000, v205
	v_pk_fma_f32 v[60:61], v[162:163], s[88:89], v[60:61] op_sel_hi:[1,0,1]
	v_pk_fma_f32 v[62:63], v[164:165], s[88:89], v[62:63] op_sel_hi:[1,0,1]
	global_store_dwordx4 v[244:245], v[60:63], off offset:0
	s_waitcnt vmcnt(31)
	v_lshlrev_b32_e32 v240, 16, v206
	v_and_b32_e32 v241, 0xffff0000, v206
	v_lshlrev_b32_e32 v242, 16, v207
	v_and_b32_e32 v243, 0xffff0000, v207
	v_pk_fma_f32 v[56:57], v[240:241], s[88:89], v[56:57] op_sel_hi:[1,0,1]
	v_pk_fma_f32 v[58:59], v[242:243], s[88:89], v[58:59] op_sel_hi:[1,0,1]
	global_store_dwordx4 v[244:245], v[56:59], off offset:16
	s_waitcnt vmcnt(31)
	v_lshlrev_b32_e32 v162, 16, v208
	v_and_b32_e32 v163, 0xffff0000, v208
	v_lshlrev_b32_e32 v164, 16, v209
	v_and_b32_e32 v165, 0xffff0000, v209
	v_pk_fma_f32 v[52:53], v[162:163], s[88:89], v[52:53] op_sel_hi:[1,0,1]
	v_pk_fma_f32 v[54:55], v[164:165], s[88:89], v[54:55] op_sel_hi:[1,0,1]
	global_store_dwordx4 v[244:245], v[52:55], off offset:512
	s_waitcnt vmcnt(31)
	v_lshlrev_b32_e32 v240, 16, v210
	v_and_b32_e32 v241, 0xffff0000, v210
	v_lshlrev_b32_e32 v242, 16, v211
	v_and_b32_e32 v243, 0xffff0000, v211
	v_pk_fma_f32 v[48:49], v[240:241], s[88:89], v[48:49] op_sel_hi:[1,0,1]
	v_pk_fma_f32 v[50:51], v[242:243], s[88:89], v[50:51] op_sel_hi:[1,0,1]
	global_store_dwordx4 v[244:245], v[48:51], off offset:528
	s_mov_b64 s[100:101], 0x120000
	v_lshl_add_u64 v[244:245], v[168:169], 0, s[100:101]
	s_waitcnt vmcnt(31)
	v_lshlrev_b32_e32 v162, 16, v212
	v_and_b32_e32 v163, 0xffff0000, v212
	v_lshlrev_b32_e32 v164, 16, v213
	v_and_b32_e32 v165, 0xffff0000, v213
	v_pk_fma_f32 v[44:45], v[162:163], s[88:89], v[44:45] op_sel_hi:[1,0,1]
	v_pk_fma_f32 v[46:47], v[164:165], s[88:89], v[46:47] op_sel_hi:[1,0,1]
	global_store_dwordx4 v[244:245], v[44:47], off offset:0
	s_waitcnt vmcnt(31)
	v_lshlrev_b32_e32 v240, 16, v214
	v_and_b32_e32 v241, 0xffff0000, v214
	v_lshlrev_b32_e32 v242, 16, v215
	v_and_b32_e32 v243, 0xffff0000, v215
	v_pk_fma_f32 v[40:41], v[240:241], s[88:89], v[40:41] op_sel_hi:[1,0,1]
	v_pk_fma_f32 v[42:43], v[242:243], s[88:89], v[42:43] op_sel_hi:[1,0,1]
	global_store_dwordx4 v[244:245], v[40:43], off offset:16
	s_waitcnt vmcnt(31)
	v_lshlrev_b32_e32 v162, 16, v216
	v_and_b32_e32 v163, 0xffff0000, v216
	v_lshlrev_b32_e32 v164, 16, v217
	v_and_b32_e32 v165, 0xffff0000, v217
	v_pk_fma_f32 v[36:37], v[162:163], s[88:89], v[36:37] op_sel_hi:[1,0,1]
	v_pk_fma_f32 v[38:39], v[164:165], s[88:89], v[38:39] op_sel_hi:[1,0,1]
	global_store_dwordx4 v[244:245], v[36:39], off offset:512
	s_waitcnt vmcnt(31)
	v_lshlrev_b32_e32 v240, 16, v218
	v_and_b32_e32 v241, 0xffff0000, v218
	v_lshlrev_b32_e32 v242, 16, v219
	v_and_b32_e32 v243, 0xffff0000, v219
	v_pk_fma_f32 v[32:33], v[240:241], s[88:89], v[32:33] op_sel_hi:[1,0,1]
	v_pk_fma_f32 v[34:35], v[242:243], s[88:89], v[34:35] op_sel_hi:[1,0,1]
	global_store_dwordx4 v[244:245], v[32:35], off offset:528
	s_mov_b64 s[100:101], 0x140000
	v_lshl_add_u64 v[244:245], v[168:169], 0, s[100:101]
	s_waitcnt vmcnt(31)
	v_lshlrev_b32_e32 v162, 16, v220
	v_and_b32_e32 v163, 0xffff0000, v220
	v_lshlrev_b32_e32 v164, 16, v221
	v_and_b32_e32 v165, 0xffff0000, v221
	v_pk_fma_f32 v[28:29], v[162:163], s[88:89], v[28:29] op_sel_hi:[1,0,1]
	v_pk_fma_f32 v[30:31], v[164:165], s[88:89], v[30:31] op_sel_hi:[1,0,1]
	global_store_dwordx4 v[244:245], v[28:31], off offset:0
	s_waitcnt vmcnt(31)
	v_lshlrev_b32_e32 v240, 16, v222
	v_and_b32_e32 v241, 0xffff0000, v222
	v_lshlrev_b32_e32 v242, 16, v223
	v_and_b32_e32 v243, 0xffff0000, v223
	v_pk_fma_f32 v[24:25], v[240:241], s[88:89], v[24:25] op_sel_hi:[1,0,1]
	v_pk_fma_f32 v[26:27], v[242:243], s[88:89], v[26:27] op_sel_hi:[1,0,1]
	global_store_dwordx4 v[244:245], v[24:27], off offset:16
	s_waitcnt vmcnt(31)
	v_lshlrev_b32_e32 v162, 16, v224
	v_and_b32_e32 v163, 0xffff0000, v224
	v_lshlrev_b32_e32 v164, 16, v225
	v_and_b32_e32 v165, 0xffff0000, v225
	v_pk_fma_f32 v[20:21], v[162:163], s[88:89], v[20:21] op_sel_hi:[1,0,1]
	v_pk_fma_f32 v[22:23], v[164:165], s[88:89], v[22:23] op_sel_hi:[1,0,1]
	global_store_dwordx4 v[244:245], v[20:23], off offset:512
	s_waitcnt vmcnt(31)
	v_lshlrev_b32_e32 v240, 16, v226
	v_and_b32_e32 v241, 0xffff0000, v226
	v_lshlrev_b32_e32 v242, 16, v227
	v_and_b32_e32 v243, 0xffff0000, v227
	v_pk_fma_f32 v[16:17], v[240:241], s[88:89], v[16:17] op_sel_hi:[1,0,1]
	v_pk_fma_f32 v[18:19], v[242:243], s[88:89], v[18:19] op_sel_hi:[1,0,1]
	global_store_dwordx4 v[244:245], v[16:19], off offset:528
	s_mov_b64 s[100:101], 0x160000
	v_lshl_add_u64 v[244:245], v[168:169], 0, s[100:101]
	s_waitcnt vmcnt(31)
	v_lshlrev_b32_e32 v162, 16, v228
	v_and_b32_e32 v163, 0xffff0000, v228
	v_lshlrev_b32_e32 v164, 16, v229
	v_and_b32_e32 v165, 0xffff0000, v229
	v_pk_fma_f32 v[12:13], v[162:163], s[88:89], v[12:13] op_sel_hi:[1,0,1]
	v_pk_fma_f32 v[14:15], v[164:165], s[88:89], v[14:15] op_sel_hi:[1,0,1]
	global_store_dwordx4 v[244:245], v[12:15], off offset:0
	s_waitcnt vmcnt(31)
	v_lshlrev_b32_e32 v240, 16, v232
	v_and_b32_e32 v241, 0xffff0000, v232
	v_lshlrev_b32_e32 v242, 16, v233
	v_and_b32_e32 v243, 0xffff0000, v233
	v_pk_fma_f32 v[8:9], v[240:241], s[88:89], v[8:9] op_sel_hi:[1,0,1]
	v_pk_fma_f32 v[10:11], v[242:243], s[88:89], v[10:11] op_sel_hi:[1,0,1]
	global_store_dwordx4 v[244:245], v[8:11], off offset:16
	s_waitcnt vmcnt(31)
	v_lshlrev_b32_e32 v162, 16, v234
	v_and_b32_e32 v163, 0xffff0000, v234
	v_lshlrev_b32_e32 v164, 16, v235
	v_and_b32_e32 v165, 0xffff0000, v235
	v_pk_fma_f32 v[4:5], v[162:163], s[88:89], v[4:5] op_sel_hi:[1,0,1]
	v_pk_fma_f32 v[6:7], v[164:165], s[88:89], v[6:7] op_sel_hi:[1,0,1]
	global_store_dwordx4 v[244:245], v[4:7], off offset:512
	s_waitcnt vmcnt(31)
	v_lshlrev_b32_e32 v240, 16, v236
	v_and_b32_e32 v241, 0xffff0000, v236
	v_lshlrev_b32_e32 v242, 16, v237
	v_and_b32_e32 v243, 0xffff0000, v237
	v_pk_fma_f32 v[0:1], v[240:241], s[88:89], v[0:1] op_sel_hi:[1,0,1]
	v_pk_fma_f32 v[2:3], v[242:243], s[88:89], v[2:3] op_sel_hi:[1,0,1]
	global_store_dwordx4 v[244:245], v[0:3], off offset:528
	s_branch .LBB0_2356
